# aggfuse2: in-epilogue chunk aggregates on all 512 threads (32 rows x 2 channels per thread, one load round trip, DPP quad combine); P2c phase and its barrier removed
# baseline (speedup 1.0000x reference)
; __device__ __forceinline__ float bf_lo(unsigned w) { return __uint_as_float(w << 16); }
; __device__ __forceinline__ float bf_hi(unsigned w) { return __uint_as_float(w & 0xffff0000u); }
;     __device__ __forceinline__ void operator()(EPI_ARGS) const {
;         const int c0 = (u.pn >> 1) * 256 + (u.pn & 1) * 128 + wc * 32 + 8 * fq;
;         u32x4 vv[2][4];
; #pragma unroll
;         for (int ai = 0; ai < 2; ++ai)
; #pragma unroll
;             for (int m = 0; m < 4; ++m) vv[ai][m] = *(const u32x4*)(V + (size_t)ROW_OF(ai, m) * LW + c0);
;         f32x4 ba[2], bi[2], sp[2];
; #pragma unroll
;         for (int n = 0; n < 2; ++n) { ba[n] = *(const f32x4*)(b_a + c0 + 4 * n); bi[n] = *(const f32x4*)(b_i + c0 + 4 * n); sp[n] = *(const f32x4*)(sp8 + c0 + 4 * n); }
; #pragma unroll
;         for (int ai = 0; ai < 2; ++ai)
; #pragma unroll
;             for (int m = 0; m < 4; ++m) {
;                 const int row = ROW_OF(ai, m);
; #pragma unroll
;                 for (int n = 0; n < 2; ++n) {
;                     const unsigned w0 = n ? vv[ai][m].z : vv[ai][m].x, w1 = n ? vv[ai][m].w : vv[ai][m].y;
;                     const f32x4 vx = (f32x4){bf_lo(w0), bf_hi(w0), bf_lo(w1), bf_hi(w1)};
;                     const f32x4 r = sigmoid4(acc[ai][0][m][n] + ba[n]), ig = sigmoid4(acc[ai][1][m][n] + bi[n]);
;                     const f32x4 la = sp[n] * r * (-1.4426950409f);
;                     f32x4 av;
; #pragma unroll
;                     for (int j = 0; j < 4; ++j) av[j] = __builtin_amdgcn_exp2f(la[j]);
;                     const f32x4 om = 1.0f - av * av; f32x4 sq;
; #pragma unroll
;                     for (int j = 0; j < 4; ++j) sq[j] = __builtin_amdgcn_sqrtf(om[j]);
;                     const f32x4 bx = sq * ig * vx;
.LBB0_556:
	v_mov_b32_e32 v65, v215
	v_mov_b32_e32 v64, v216
	s_lshl_b32 s0, s27, 7
	s_or_b32 s0, s0, s21
	v_lshl_add_u32 v64, v64, 3, s0
	s_lshl_b32 s0, s74, 8
	s_add_i32 s0, s0, s19
	v_add_u32_e32 v68, s0, v65
	v_ashrrev_i32_e32 v65, 31, v64
	v_ashrrev_i32_e32 v69, 31, v68
	v_lshl_add_u64 v[70:71], v[64:65], 1, s[54:55]
	v_lshlrev_b64 v[66:67], 12, v[68:69]
	v_lshlrev_b64 v[196:197], 2, v[64:65]
	v_lshl_add_u64 v[66:67], v[70:71], 0, v[66:67]
	v_lshl_add_u64 v[64:65], s[38:39], 0, v[196:197]
	global_load_dwordx4 v[180:183], v[66:67], off
	global_load_dwordx4 v[100:103], v[64:65], off
	v_lshl_add_u64 v[66:67], s[42:43], 0, v[196:197]
	global_load_dwordx4 v[92:95], v[66:67], off
	v_lshl_add_u64 v[108:109], s[56:57], 0, v[196:197]
	global_load_dwordx4 v[88:91], v[108:109], off
	global_load_dwordx4 v[80:83], v[64:65], off offset:16
	global_load_dwordx4 v[72:75], v[66:67], off offset:16
	s_nop 0
	global_load_dwordx4 v[64:67], v[108:109], off offset:16
	v_add_u32_e32 v210, 16, v68
	v_add_u32_e32 v208, 32, v68
	v_add_u32_e32 v206, 48, v68
	v_add_u32_e32 v204, 0x80, v68
	v_add_u32_e32 v202, 0x90, v68
	v_add_u32_e32 v200, 0xa0, v68
	v_add_u32_e32 v198, 0xb0, v68
	v_ashrrev_i32_e32 v211, 31, v210
	v_ashrrev_i32_e32 v209, 31, v208
	v_ashrrev_i32_e32 v207, 31, v206
	v_ashrrev_i32_e32 v205, 31, v204
	v_ashrrev_i32_e32 v203, 31, v202
	v_ashrrev_i32_e32 v201, 31, v200
	v_ashrrev_i32_e32 v199, 31, v198
	v_lshlrev_b64 v[222:223], 13, v[68:69]
	v_lshlrev_b64 v[68:69], 12, v[210:211]
	v_lshlrev_b64 v[108:109], 12, v[208:209]
	v_lshlrev_b64 v[110:111], 12, v[206:207]
	v_lshlrev_b64 v[128:129], 12, v[204:205]
	v_lshlrev_b64 v[130:131], 12, v[202:203]
	v_lshlrev_b64 v[148:149], 12, v[200:201]
	v_lshlrev_b64 v[150:151], 12, v[198:199]
	v_lshl_add_u64 v[68:69], v[70:71], 0, v[68:69]
	v_lshl_add_u64 v[108:109], v[70:71], 0, v[108:109]
	v_lshl_add_u64 v[110:111], v[70:71], 0, v[110:111]
	v_lshl_add_u64 v[128:129], v[70:71], 0, v[128:129]
	v_lshl_add_u64 v[130:131], v[70:71], 0, v[130:131]
	v_lshl_add_u64 v[224:225], v[70:71], 0, v[148:149]
	v_lshl_add_u64 v[70:71], v[70:71], 0, v[150:151]
	global_load_dwordx4 v[176:179], v[68:69], off
	global_load_dwordx4 v[172:175], v[108:109], off
	global_load_dwordx4 v[164:167], v[110:111], off
	global_load_dwordx4 v[148:151], v[128:129], off
	s_nop 0
	global_load_dwordx4 v[128:131], v[130:131], off
	s_nop 0
	global_load_dwordx4 v[108:111], v[224:225], off
	s_nop 0
	global_load_dwordx4 v[68:71], v[70:71], off
	v_readlane_b32 s80, v248, 11
	v_readlane_b32 s92, v248, 23
	v_readlane_b32 s93, v248, 24
	v_readlane_b32 s81, v248, 12
	v_readlane_b32 s82, v248, 13
	v_readlane_b32 s83, v248, 14
	v_readlane_b32 s84, v248, 15
	v_readlane_b32 s85, v248, 16
	v_readlane_b32 s86, v248, 17
	v_readlane_b32 s87, v248, 18
	v_readlane_b32 s88, v248, 19
	v_readlane_b32 s89, v248, 20
	v_readlane_b32 s90, v248, 21
	v_readlane_b32 s91, v248, 22
	v_readlane_b32 s94, v248, 25
	v_readlane_b32 s95, v248, 26
	s_and_b64 vcc, exec, s[4:5]
	s_mov_b64 s[0:1], -1
	s_waitcnt vmcnt(0)
	v_lshlrev_b32_e32 v224, 16, v180
	v_pk_add_f32 v[168:169], v[168:169], v[100:101]
	v_pk_add_f32 v[170:171], v[170:171], v[102:103]
	v_pk_add_f32 v[160:161], v[160:161], v[92:93]
	v_mul_f32_e32 v168, 0xbfb8aa3b, v168
	v_mul_f32_e32 v169, 0xbfb8aa3b, v169
	v_mul_f32_e32 v170, 0xbfb8aa3b, v170
	v_mul_f32_e32 v171, 0xbfb8aa3b, v171
	v_mul_f32_e32 v160, 0xbfb8aa3b, v160
	v_mul_f32_e32 v161, 0xbfb8aa3b, v161
	v_exp_f32_e32 v168, v168
	v_exp_f32_e32 v169, v169
	v_pk_add_f32 v[162:163], v[162:163], v[94:95]
	v_exp_f32_e32 v170, v170
	v_exp_f32_e32 v171, v171
	v_exp_f32_e32 v160, v160
	v_exp_f32_e32 v161, v161
	v_mul_f32_e32 v162, 0xbfb8aa3b, v162
	v_mul_f32_e32 v163, 0xbfb8aa3b, v163
	v_exp_f32_e32 v162, v162
	v_and_b32_e32 v225, 0xffff0000, v180
	v_exp_f32_e32 v180, v163
	v_add_f32_e32 v163, 1.0, v168
	v_add_f32_e32 v168, 1.0, v169
	v_add_f32_e32 v169, 1.0, v170
	v_add_f32_e32 v170, 1.0, v171
	v_add_f32_e32 v171, 1.0, v160
	v_add_f32_e32 v221, 1.0, v161
	v_rcp_f32_e32 v160, v163
	v_rcp_f32_e32 v161, v168
	v_add_f32_e32 v226, 1.0, v162
	v_rcp_f32_e32 v162, v169
	v_rcp_f32_e32 v163, v170
	v_pk_mul_f32 v[160:161], v[88:89], v[160:161]
	v_rcp_f32_e32 v170, v226
	v_pk_mul_f32 v[160:161], v[160:161], s[62:63] op_sel_hi:[1,0]
	v_pk_mul_f32 v[162:163], v[90:91], v[162:163]
	v_exp_f32_e32 v226, v160
	v_exp_f32_e32 v227, v161
	v_pk_mul_f32 v[162:163], v[162:163], s[62:63] op_sel_hi:[1,0]
	v_pk_add_f32 v[156:157], v[156:157], v[80:81]
	v_exp_f32_e32 v228, v162
	v_exp_f32_e32 v229, v163
	v_pk_add_f32 v[158:159], v[158:159], v[82:83]
	v_mul_f32_e32 v156, 0xbfb8aa3b, v156
	v_mul_f32_e32 v157, 0xbfb8aa3b, v157
	v_pk_mul_f32 v[226:227], v[226:227], v[226:227]
	v_exp_f32_e32 v156, v156
	v_exp_f32_e32 v157, v157
	v_mul_f32_e32 v158, 0xbfb8aa3b, v158
	v_mul_f32_e32 v159, 0xbfb8aa3b, v159
	v_rcp_f32_e32 v168, v171
	v_add_f32_e32 v171, 1.0, v180
	v_sub_f32_e32 v180, 1.0, v226
	v_exp_f32_e32 v158, v158
	v_exp_f32_e32 v159, v159
	v_pk_mul_f32 v[228:229], v[228:229], v[228:229]
	v_sqrt_f32_e32 v226, v180
	v_sub_f32_e32 v180, 1.0, v227
	v_rcp_f32_e32 v169, v221
	v_sub_f32_e32 v221, 1.0, v228
	v_sqrt_f32_e32 v227, v180
	v_sqrt_f32_e32 v228, v221
	v_sub_f32_e32 v221, 1.0, v229
	v_add_f32_e32 v156, 1.0, v156
	v_add_f32_e32 v157, 1.0, v157
	v_rcp_f32_e32 v171, v171
	v_sqrt_f32_e32 v229, v221
	v_rcp_f32_e32 v156, v156
	v_rcp_f32_e32 v157, v157
	v_add_f32_e32 v158, 1.0, v158
	v_add_f32_e32 v159, 1.0, v159
	v_rcp_f32_e32 v158, v158
	v_rcp_f32_e32 v159, v159
	v_pk_mul_f32 v[168:169], v[168:169], v[226:227]
	v_lshlrev_b32_e32 v180, 16, v181
	v_pk_mul_f32 v[168:169], v[168:169], v[224:225]
	v_and_b32_e32 v181, 0xffff0000, v181
; __device__ __forceinline__ unsigned cvt_pk_bf16(float lo, float hi) { unsigned r; asm volatile("v_cvt_pk_bf16_f32 %0, %1, %2" : "=v"(r) : "v"(lo), "v"(hi)); return r; }
; __device__ __forceinline__ float bf_lo(unsigned w) { return __uint_as_float(w << 16); }
; __device__ __forceinline__ float bf_hi(unsigned w) { return __uint_as_float(w & 0xffff0000u); }
;     __device__ __forceinline__ void operator()(EPI_ARGS) const {
;     ...
;         for (int ai = 0; ai < 2; ++ai)
; #pragma unroll
;             for (int m = 0; m < 4; ++m) {
;                 const int row = ROW_OF(ai, m);
; #pragma unroll
;                 for (int n = 0; n < 2; ++n) {
;                     const unsigned w0 = n ? vv[ai][m].z : vv[ai][m].x, w1 = n ? vv[ai][m].w : vv[ai][m].y;
;                     const f32x4 vx = (f32x4){bf_lo(w0), bf_hi(w0), bf_lo(w1), bf_hi(w1)};
;                     const f32x4 r = sigmoid4(acc[ai][0][m][n] + ba[n]), ig = sigmoid4(acc[ai][1][m][n] + bi[n]);
;                     const f32x4 la = sp[n] * r * (-1.4426950409f);
;                     f32x4 av;
; #pragma unroll
;                     for (int j = 0; j < 4; ++j) av[j] = __builtin_amdgcn_exp2f(la[j]);
;                     const f32x4 om = 1.0f - av * av; f32x4 sq;
; #pragma unroll
;                     for (int j = 0; j < 4; ++j) sq[j] = __builtin_amdgcn_sqrtf(om[j]);
;                     const f32x4 bx = sq * ig * vx;
;                     u32x4 w; w.x = cvt_pk_bf16(la[0], bx[0]); w.y = cvt_pk_bf16(la[1], bx[1]); w.z = cvt_pk_bf16(la[2], bx[2]); w.w = cvt_pk_bf16(la[3], bx[3]);
;                     *(u32x4*)(AB + (size_t)row * LW + c0 + 4 * n) = w;
	v_pk_mul_f32 v[170:171], v[170:171], v[228:229]
	v_cvt_pk_bf16_f32 v160, v160, v168
	v_cvt_pk_bf16_f32 v161, v161, v169
	v_lshl_add_u64 v[168:169], s[92:93], 0, v[222:223]
	v_pk_mul_f32 v[156:157], v[64:65], v[156:157]
	v_pk_mul_f32 v[170:171], v[170:171], v[180:181]
	v_lshl_add_u64 v[168:169], v[168:169], 0, v[196:197]
	v_cvt_pk_bf16_f32 v162, v162, v170
	v_cvt_pk_bf16_f32 v163, v163, v171
	v_pk_add_f32 v[152:153], v[152:153], v[72:73]
	v_pk_mul_f32 v[158:159], v[66:67], v[158:159]
	v_pk_mul_f32 v[156:157], v[156:157], s[62:63] op_sel_hi:[1,0]
	v_pk_add_f32 v[144:145], v[144:145], v[100:101]
	global_store_dwordx4 v[168:169], v[160:163], off
	v_pk_add_f32 v[154:155], v[154:155], v[74:75]
	v_mul_f32_e32 v152, 0xbfb8aa3b, v152
	v_mul_f32_e32 v153, 0xbfb8aa3b, v153
	v_pk_mul_f32 v[158:159], v[158:159], s[62:63] op_sel_hi:[1,0]
	v_exp_f32_e32 v162, v156
	v_exp_f32_e32 v163, v157
	v_pk_add_f32 v[146:147], v[146:147], v[102:103]
	v_mul_f32_e32 v144, 0xbfb8aa3b, v144
	v_mul_f32_e32 v145, 0xbfb8aa3b, v145
	v_exp_f32_e32 v152, v152
	v_exp_f32_e32 v153, v153
	v_mul_f32_e32 v154, 0xbfb8aa3b, v154
	v_mul_f32_e32 v155, 0xbfb8aa3b, v155
	v_exp_f32_e32 v170, v158
	v_exp_f32_e32 v171, v159
	v_exp_f32_e32 v144, v144
	v_exp_f32_e32 v145, v145
	v_mul_f32_e32 v146, 0xbfb8aa3b, v146
	v_mul_f32_e32 v147, 0xbfb8aa3b, v147
	v_exp_f32_e32 v154, v154
	v_exp_f32_e32 v155, v155
	v_exp_f32_e32 v146, v146
	v_exp_f32_e32 v147, v147
	v_pk_mul_f32 v[162:163], v[162:163], v[162:163]
	v_add_f32_e32 v152, 1.0, v152
	v_add_f32_e32 v153, 1.0, v153
	v_pk_mul_f32 v[170:171], v[170:171], v[170:171]
	v_sub_f32_e32 v162, 1.0, v162
	v_sub_f32_e32 v163, 1.0, v163
	v_add_f32_e32 v144, 1.0, v144
	v_add_f32_e32 v145, 1.0, v145
	v_rcp_f32_e32 v152, v152
	v_rcp_f32_e32 v153, v153
	v_add_f32_e32 v154, 1.0, v154
	v_add_f32_e32 v155, 1.0, v155
	v_sqrt_f32_e32 v162, v162
	v_sub_f32_e32 v170, 1.0, v170
	v_sub_f32_e32 v171, 1.0, v171
	v_sqrt_f32_e32 v163, v163
	v_rcp_f32_e32 v144, v144
	v_rcp_f32_e32 v145, v145
	v_add_f32_e32 v146, 1.0, v146
	v_add_f32_e32 v147, 1.0, v147
	v_rcp_f32_e32 v154, v154
	v_rcp_f32_e32 v155, v155
	v_sqrt_f32_e32 v170, v170
	v_sqrt_f32_e32 v171, v171
	v_rcp_f32_e32 v146, v146
	v_rcp_f32_e32 v147, v147
	v_lshlrev_b32_e32 v160, 16, v182
	v_and_b32_e32 v161, 0xffff0000, v182
	v_pk_mul_f32 v[152:153], v[152:153], v[162:163]
	v_pk_mul_f32 v[144:145], v[88:89], v[144:145]
	v_lshlrev_b32_e32 v180, 16, v183
	v_and_b32_e32 v181, 0xffff0000, v183
	v_pk_mul_f32 v[154:155], v[154:155], v[170:171]
	v_pk_mul_f32 v[152:153], v[152:153], v[160:161]
	v_pk_add_f32 v[140:141], v[140:141], v[92:93]
	v_pk_mul_f32 v[146:147], v[90:91], v[146:147]
	v_pk_mul_f32 v[144:145], v[144:145], s[62:63] op_sel_hi:[1,0]
	v_pk_mul_f32 v[154:155], v[154:155], v[180:181]
	v_cvt_pk_bf16_f32 v152, v156, v152
	v_cvt_pk_bf16_f32 v153, v157, v153
	v_pk_add_f32 v[142:143], v[142:143], v[94:95]
	v_mul_f32_e32 v140, 0xbfb8aa3b, v140
	v_mul_f32_e32 v141, 0xbfb8aa3b, v141
	v_pk_mul_f32 v[146:147], v[146:147], s[62:63] op_sel_hi:[1,0]
	v_exp_f32_e32 v156, v144
	v_exp_f32_e32 v157, v145
	v_cvt_pk_bf16_f32 v154, v158, v154
	v_cvt_pk_bf16_f32 v155, v159, v155
	v_exp_f32_e32 v140, v140
	v_exp_f32_e32 v141, v141
	v_mul_f32_e32 v142, 0xbfb8aa3b, v142
	v_mul_f32_e32 v143, 0xbfb8aa3b, v143
	v_exp_f32_e32 v158, v146
	v_exp_f32_e32 v159, v147
	v_pk_add_f32 v[136:137], v[136:137], v[80:81]
	v_exp_f32_e32 v142, v142
	v_exp_f32_e32 v143, v143
	v_pk_add_f32 v[138:139], v[138:139], v[82:83]
	v_mul_f32_e32 v136, 0xbfb8aa3b, v136
	v_mul_f32_e32 v137, 0xbfb8aa3b, v137
	v_exp_f32_e32 v136, v136
	v_exp_f32_e32 v137, v137
	v_mul_f32_e32 v138, 0xbfb8aa3b, v138
	v_mul_f32_e32 v139, 0xbfb8aa3b, v139
	v_pk_mul_f32 v[156:157], v[156:157], v[156:157]
	v_exp_f32_e32 v138, v138
	v_exp_f32_e32 v139, v139
	v_add_f32_e32 v140, 1.0, v140
	v_add_f32_e32 v141, 1.0, v141
	v_pk_mul_f32 v[158:159], v[158:159], v[158:159]
	v_sub_f32_e32 v156, 1.0, v156
	v_sub_f32_e32 v157, 1.0, v157
	v_rcp_f32_e32 v140, v140
	v_rcp_f32_e32 v141, v141
	v_add_f32_e32 v142, 1.0, v142
	v_add_f32_e32 v143, 1.0, v143
	v_sqrt_f32_e32 v156, v156
	v_sub_f32_e32 v158, 1.0, v158
	v_sub_f32_e32 v159, 1.0, v159
	v_sqrt_f32_e32 v157, v157
	v_rcp_f32_e32 v142, v142
	v_rcp_f32_e32 v143, v143
	v_sqrt_f32_e32 v158, v158
	v_sqrt_f32_e32 v159, v159
	v_add_f32_e32 v136, 1.0, v136
	v_add_f32_e32 v137, 1.0, v137
	v_rcp_f32_e32 v136, v136
	v_rcp_f32_e32 v137, v137
	v_add_f32_e32 v138, 1.0, v138
	v_add_f32_e32 v139, 1.0, v139
	v_rcp_f32_e32 v138, v138
	v_rcp_f32_e32 v139, v139
	global_store_dwordx4 v[168:169], v[152:155], off offset:16
	v_pk_mul_f32 v[140:141], v[140:141], v[156:157]
	v_lshlrev_b32_e32 v160, 16, v177
	v_lshlrev_b32_e32 v154, 16, v176
	v_and_b32_e32 v155, 0xffff0000, v176
	v_lshlrev_b64 v[152:153], 13, v[210:211]
	v_and_b32_e32 v161, 0xffff0000, v177
	v_pk_mul_f32 v[142:143], v[142:143], v[158:159]
	v_pk_mul_f32 v[140:141], v[140:141], v[154:155]
	v_pk_mul_f32 v[142:143], v[142:143], v[160:161]
	v_cvt_pk_bf16_f32 v140, v144, v140
	v_cvt_pk_bf16_f32 v141, v145, v141
	v_lshl_add_u64 v[144:145], s[92:93], 0, v[152:153]
	v_pk_mul_f32 v[136:137], v[64:65], v[136:137]
	v_cvt_pk_bf16_f32 v142, v146, v142
	v_cvt_pk_bf16_f32 v143, v147, v143
	v_lshl_add_u64 v[144:145], v[144:145], 0, v[196:197]
	v_pk_add_f32 v[132:133], v[132:133], v[72:73]
	v_pk_mul_f32 v[138:139], v[66:67], v[138:139]
	v_pk_mul_f32 v[136:137], v[136:137], s[62:63] op_sel_hi:[1,0]
	v_pk_add_f32 v[124:125], v[124:125], v[100:101]
	global_store_dwordx4 v[144:145], v[140:143], off
	v_pk_add_f32 v[134:135], v[134:135], v[74:75]
	v_mul_f32_e32 v132, 0xbfb8aa3b, v132
	v_mul_f32_e32 v133, 0xbfb8aa3b, v133
; __device__ __forceinline__ unsigned cvt_pk_bf16(float lo, float hi) { unsigned r; asm volatile("v_cvt_pk_bf16_f32 %0, %1, %2" : "=v"(r) : "v"(lo), "v"(hi)); return r; }
; __device__ __forceinline__ float bf_lo(unsigned w) { return __uint_as_float(w << 16); }
; __device__ __forceinline__ float bf_hi(unsigned w) { return __uint_as_float(w & 0xffff0000u); }
;     __device__ __forceinline__ void operator()(EPI_ARGS) const {
;     ...
; #pragma unroll
;         for (int ai = 0; ai < 2; ++ai)
; #pragma unroll
;             for (int m = 0; m < 4; ++m) {
;                 const int row = ROW_OF(ai, m);
; #pragma unroll
;                 for (int n = 0; n < 2; ++n) {
;                     const unsigned w0 = n ? vv[ai][m].z : vv[ai][m].x, w1 = n ? vv[ai][m].w : vv[ai][m].y;
;                     const f32x4 vx = (f32x4){bf_lo(w0), bf_hi(w0), bf_lo(w1), bf_hi(w1)};
;                     const f32x4 r = sigmoid4(acc[ai][0][m][n] + ba[n]), ig = sigmoid4(acc[ai][1][m][n] + bi[n]);
;                     const f32x4 la = sp[n] * r * (-1.4426950409f);
;                     f32x4 av;
; #pragma unroll
;                     for (int j = 0; j < 4; ++j) av[j] = __builtin_amdgcn_exp2f(la[j]);
;                     const f32x4 om = 1.0f - av * av; f32x4 sq;
; #pragma unroll
;                     for (int j = 0; j < 4; ++j) sq[j] = __builtin_amdgcn_sqrtf(om[j]);
;                     const f32x4 bx = sq * ig * vx;
;                     u32x4 w; w.x = cvt_pk_bf16(la[0], bx[0]); w.y = cvt_pk_bf16(la[1], bx[1]); w.z = cvt_pk_bf16(la[2], bx[2]); w.w = cvt_pk_bf16(la[3], bx[3]);
;                     *(u32x4*)(AB + (size_t)row * LW + c0 + 4 * n) = w;
	v_pk_mul_f32 v[138:139], v[138:139], s[62:63] op_sel_hi:[1,0]
	v_exp_f32_e32 v142, v136
	v_exp_f32_e32 v143, v137
	v_pk_add_f32 v[126:127], v[126:127], v[102:103]
	v_mul_f32_e32 v124, 0xbfb8aa3b, v124
	v_mul_f32_e32 v125, 0xbfb8aa3b, v125
	v_exp_f32_e32 v132, v132
	v_exp_f32_e32 v133, v133
	v_mul_f32_e32 v134, 0xbfb8aa3b, v134
	v_mul_f32_e32 v135, 0xbfb8aa3b, v135
	v_exp_f32_e32 v146, v138
	v_exp_f32_e32 v147, v139
	v_exp_f32_e32 v124, v124
	v_exp_f32_e32 v125, v125
	v_mul_f32_e32 v126, 0xbfb8aa3b, v126
	v_mul_f32_e32 v127, 0xbfb8aa3b, v127
	v_exp_f32_e32 v134, v134
	v_exp_f32_e32 v135, v135
	v_exp_f32_e32 v126, v126
	v_exp_f32_e32 v127, v127
	v_pk_mul_f32 v[142:143], v[142:143], v[142:143]
	v_add_f32_e32 v132, 1.0, v132
	v_add_f32_e32 v133, 1.0, v133
	v_pk_mul_f32 v[146:147], v[146:147], v[146:147]
	v_sub_f32_e32 v142, 1.0, v142
	v_sub_f32_e32 v143, 1.0, v143
	v_add_f32_e32 v124, 1.0, v124
	v_add_f32_e32 v125, 1.0, v125
	v_rcp_f32_e32 v132, v132
	v_rcp_f32_e32 v133, v133
	v_add_f32_e32 v134, 1.0, v134
	v_add_f32_e32 v135, 1.0, v135
	v_sqrt_f32_e32 v142, v142
	v_sub_f32_e32 v146, 1.0, v146
	v_sub_f32_e32 v147, 1.0, v147
	v_sqrt_f32_e32 v143, v143
	v_rcp_f32_e32 v124, v124
	v_rcp_f32_e32 v125, v125
	v_add_f32_e32 v126, 1.0, v126
	v_add_f32_e32 v127, 1.0, v127
	v_rcp_f32_e32 v134, v134
	v_rcp_f32_e32 v135, v135
	v_sqrt_f32_e32 v146, v146
	v_sqrt_f32_e32 v147, v147
	v_rcp_f32_e32 v126, v126
	v_rcp_f32_e32 v127, v127
	v_lshlrev_b32_e32 v140, 16, v178
	v_and_b32_e32 v141, 0xffff0000, v178
	v_pk_mul_f32 v[132:133], v[132:133], v[142:143]
	v_pk_mul_f32 v[124:125], v[88:89], v[124:125]
	v_lshlrev_b32_e32 v152, 16, v179
	v_and_b32_e32 v153, 0xffff0000, v179
	v_pk_mul_f32 v[134:135], v[134:135], v[146:147]
	v_pk_mul_f32 v[132:133], v[132:133], v[140:141]
	v_pk_add_f32 v[120:121], v[120:121], v[92:93]
	v_pk_mul_f32 v[126:127], v[90:91], v[126:127]
	v_pk_mul_f32 v[124:125], v[124:125], s[62:63] op_sel_hi:[1,0]
	v_pk_mul_f32 v[134:135], v[134:135], v[152:153]
	v_cvt_pk_bf16_f32 v132, v136, v132
	v_cvt_pk_bf16_f32 v133, v137, v133
	v_pk_add_f32 v[122:123], v[122:123], v[94:95]
	v_mul_f32_e32 v120, 0xbfb8aa3b, v120
	v_mul_f32_e32 v121, 0xbfb8aa3b, v121
	v_pk_mul_f32 v[126:127], v[126:127], s[62:63] op_sel_hi:[1,0]
	v_exp_f32_e32 v136, v124
	v_exp_f32_e32 v137, v125
	v_cvt_pk_bf16_f32 v134, v138, v134
	v_cvt_pk_bf16_f32 v135, v139, v135
	v_exp_f32_e32 v120, v120
	v_exp_f32_e32 v121, v121
	v_mul_f32_e32 v122, 0xbfb8aa3b, v122
	v_mul_f32_e32 v123, 0xbfb8aa3b, v123
	v_exp_f32_e32 v138, v126
	v_exp_f32_e32 v139, v127
	v_pk_add_f32 v[116:117], v[116:117], v[80:81]
	v_exp_f32_e32 v122, v122
	v_exp_f32_e32 v123, v123
	v_pk_add_f32 v[118:119], v[118:119], v[82:83]
	v_mul_f32_e32 v116, 0xbfb8aa3b, v116
	v_mul_f32_e32 v117, 0xbfb8aa3b, v117
	v_exp_f32_e32 v116, v116
	v_exp_f32_e32 v117, v117
	v_mul_f32_e32 v118, 0xbfb8aa3b, v118
	v_mul_f32_e32 v119, 0xbfb8aa3b, v119
	v_pk_mul_f32 v[136:137], v[136:137], v[136:137]
	v_exp_f32_e32 v118, v118
	v_exp_f32_e32 v119, v119
	v_add_f32_e32 v120, 1.0, v120
	v_add_f32_e32 v121, 1.0, v121
	v_pk_mul_f32 v[138:139], v[138:139], v[138:139]
	v_sub_f32_e32 v136, 1.0, v136
	v_sub_f32_e32 v137, 1.0, v137
	v_rcp_f32_e32 v120, v120
	v_rcp_f32_e32 v121, v121
	v_add_f32_e32 v122, 1.0, v122
	v_add_f32_e32 v123, 1.0, v123
	v_sqrt_f32_e32 v136, v136
	v_sub_f32_e32 v138, 1.0, v138
	v_sub_f32_e32 v139, 1.0, v139
	v_sqrt_f32_e32 v137, v137
	v_rcp_f32_e32 v122, v122
	v_rcp_f32_e32 v123, v123
	v_sqrt_f32_e32 v138, v138
	v_sqrt_f32_e32 v139, v139
	v_add_f32_e32 v116, 1.0, v116
	v_add_f32_e32 v117, 1.0, v117
	v_rcp_f32_e32 v116, v116
	v_rcp_f32_e32 v117, v117
	v_add_f32_e32 v118, 1.0, v118
	v_add_f32_e32 v119, 1.0, v119
	v_rcp_f32_e32 v118, v118
	v_rcp_f32_e32 v119, v119
	global_store_dwordx4 v[144:145], v[132:135], off offset:16
	v_pk_mul_f32 v[120:121], v[120:121], v[136:137]
	v_lshlrev_b32_e32 v140, 16, v173
	v_lshlrev_b32_e32 v134, 16, v172
	v_and_b32_e32 v135, 0xffff0000, v172
	v_lshlrev_b64 v[132:133], 13, v[208:209]
	v_and_b32_e32 v141, 0xffff0000, v173
	v_pk_mul_f32 v[122:123], v[122:123], v[138:139]
	v_pk_mul_f32 v[120:121], v[120:121], v[134:135]
	v_pk_mul_f32 v[122:123], v[122:123], v[140:141]
	v_cvt_pk_bf16_f32 v120, v124, v120
	v_cvt_pk_bf16_f32 v121, v125, v121
	v_lshl_add_u64 v[124:125], s[92:93], 0, v[132:133]
	v_pk_mul_f32 v[116:117], v[64:65], v[116:117]
	v_cvt_pk_bf16_f32 v122, v126, v122
	v_cvt_pk_bf16_f32 v123, v127, v123
	v_lshl_add_u64 v[124:125], v[124:125], 0, v[196:197]
	v_pk_add_f32 v[112:113], v[112:113], v[72:73]
	v_pk_mul_f32 v[118:119], v[66:67], v[118:119]
	v_pk_mul_f32 v[116:117], v[116:117], s[62:63] op_sel_hi:[1,0]
	v_pk_add_f32 v[104:105], v[104:105], v[100:101]
	global_store_dwordx4 v[124:125], v[120:123], off
	v_pk_add_f32 v[114:115], v[114:115], v[74:75]
	v_mul_f32_e32 v112, 0xbfb8aa3b, v112
	v_mul_f32_e32 v113, 0xbfb8aa3b, v113
	v_pk_mul_f32 v[118:119], v[118:119], s[62:63] op_sel_hi:[1,0]
	v_exp_f32_e32 v122, v116
	v_exp_f32_e32 v123, v117
	v_pk_add_f32 v[106:107], v[106:107], v[102:103]
	v_mul_f32_e32 v104, 0xbfb8aa3b, v104
	v_mul_f32_e32 v105, 0xbfb8aa3b, v105
	v_exp_f32_e32 v112, v112
	v_exp_f32_e32 v113, v113
	v_mul_f32_e32 v114, 0xbfb8aa3b, v114
	v_mul_f32_e32 v115, 0xbfb8aa3b, v115
	v_exp_f32_e32 v126, v118
	v_exp_f32_e32 v127, v119
	v_exp_f32_e32 v104, v104
	v_exp_f32_e32 v105, v105
	v_mul_f32_e32 v106, 0xbfb8aa3b, v106
	v_mul_f32_e32 v107, 0xbfb8aa3b, v107
	v_exp_f32_e32 v114, v114
	v_exp_f32_e32 v115, v115
	v_exp_f32_e32 v106, v106
	v_exp_f32_e32 v107, v107
	v_pk_mul_f32 v[122:123], v[122:123], v[122:123]
	v_add_f32_e32 v112, 1.0, v112
	v_add_f32_e32 v113, 1.0, v113
	v_pk_mul_f32 v[126:127], v[126:127], v[126:127]
; __device__ __forceinline__ unsigned cvt_pk_bf16(float lo, float hi) { unsigned r; asm volatile("v_cvt_pk_bf16_f32 %0, %1, %2" : "=v"(r) : "v"(lo), "v"(hi)); return r; }
; __device__ __forceinline__ float bf_lo(unsigned w) { return __uint_as_float(w << 16); }
; __device__ __forceinline__ float bf_hi(unsigned w) { return __uint_as_float(w & 0xffff0000u); }
;     __device__ __forceinline__ void operator()(EPI_ARGS) const {
;     ...
; #pragma unroll
;         for (int ai = 0; ai < 2; ++ai)
; #pragma unroll
;             for (int m = 0; m < 4; ++m) {
;                 const int row = ROW_OF(ai, m);
; #pragma unroll
;                 for (int n = 0; n < 2; ++n) {
;                     const unsigned w0 = n ? vv[ai][m].z : vv[ai][m].x, w1 = n ? vv[ai][m].w : vv[ai][m].y;
;                     const f32x4 vx = (f32x4){bf_lo(w0), bf_hi(w0), bf_lo(w1), bf_hi(w1)};
;                     const f32x4 r = sigmoid4(acc[ai][0][m][n] + ba[n]), ig = sigmoid4(acc[ai][1][m][n] + bi[n]);
;                     const f32x4 la = sp[n] * r * (-1.4426950409f);
;                     f32x4 av;
; #pragma unroll
;                     for (int j = 0; j < 4; ++j) av[j] = __builtin_amdgcn_exp2f(la[j]);
;                     const f32x4 om = 1.0f - av * av; f32x4 sq;
; #pragma unroll
;                     for (int j = 0; j < 4; ++j) sq[j] = __builtin_amdgcn_sqrtf(om[j]);
;                     const f32x4 bx = sq * ig * vx;
;                     u32x4 w; w.x = cvt_pk_bf16(la[0], bx[0]); w.y = cvt_pk_bf16(la[1], bx[1]); w.z = cvt_pk_bf16(la[2], bx[2]); w.w = cvt_pk_bf16(la[3], bx[3]);
;                     *(u32x4*)(AB + (size_t)row * LW + c0 + 4 * n) = w;
	v_sub_f32_e32 v122, 1.0, v122
	v_sub_f32_e32 v123, 1.0, v123
	v_add_f32_e32 v104, 1.0, v104
	v_add_f32_e32 v105, 1.0, v105
	v_rcp_f32_e32 v112, v112
	v_rcp_f32_e32 v113, v113
	v_add_f32_e32 v114, 1.0, v114
	v_add_f32_e32 v115, 1.0, v115
	v_sqrt_f32_e32 v122, v122
	v_sub_f32_e32 v126, 1.0, v126
	v_sub_f32_e32 v127, 1.0, v127
	v_sqrt_f32_e32 v123, v123
	v_rcp_f32_e32 v104, v104
	v_rcp_f32_e32 v105, v105
	v_add_f32_e32 v106, 1.0, v106
	v_add_f32_e32 v107, 1.0, v107
	v_rcp_f32_e32 v114, v114
	v_rcp_f32_e32 v115, v115
	v_sqrt_f32_e32 v126, v126
	v_sqrt_f32_e32 v127, v127
	v_rcp_f32_e32 v106, v106
	v_rcp_f32_e32 v107, v107
	v_lshlrev_b32_e32 v120, 16, v174
	v_and_b32_e32 v121, 0xffff0000, v174
	v_pk_mul_f32 v[112:113], v[112:113], v[122:123]
	v_pk_mul_f32 v[104:105], v[88:89], v[104:105]
	v_lshlrev_b32_e32 v132, 16, v175
	v_and_b32_e32 v133, 0xffff0000, v175
	v_pk_mul_f32 v[114:115], v[114:115], v[126:127]
	v_pk_mul_f32 v[112:113], v[112:113], v[120:121]
	v_pk_add_f32 v[96:97], v[96:97], v[92:93]
	v_pk_mul_f32 v[106:107], v[90:91], v[106:107]
	v_pk_mul_f32 v[104:105], v[104:105], s[62:63] op_sel_hi:[1,0]
	v_pk_mul_f32 v[114:115], v[114:115], v[132:133]
	v_cvt_pk_bf16_f32 v112, v116, v112
	v_cvt_pk_bf16_f32 v113, v117, v113
	v_pk_add_f32 v[98:99], v[98:99], v[94:95]
	v_mul_f32_e32 v96, 0xbfb8aa3b, v96
	v_mul_f32_e32 v97, 0xbfb8aa3b, v97
	v_pk_mul_f32 v[106:107], v[106:107], s[62:63] op_sel_hi:[1,0]
	v_exp_f32_e32 v116, v104
	v_exp_f32_e32 v117, v105
	v_cvt_pk_bf16_f32 v114, v118, v114
	v_cvt_pk_bf16_f32 v115, v119, v115
	v_exp_f32_e32 v96, v96
	v_exp_f32_e32 v97, v97
	v_mul_f32_e32 v98, 0xbfb8aa3b, v98
	v_mul_f32_e32 v99, 0xbfb8aa3b, v99
	v_exp_f32_e32 v118, v106
	v_exp_f32_e32 v119, v107
	v_pk_add_f32 v[84:85], v[84:85], v[80:81]
	v_exp_f32_e32 v98, v98
	v_exp_f32_e32 v99, v99
	v_pk_add_f32 v[86:87], v[86:87], v[82:83]
	v_mul_f32_e32 v84, 0xbfb8aa3b, v84
	v_mul_f32_e32 v85, 0xbfb8aa3b, v85
	v_exp_f32_e32 v84, v84
	v_exp_f32_e32 v85, v85
	v_mul_f32_e32 v86, 0xbfb8aa3b, v86
	v_mul_f32_e32 v87, 0xbfb8aa3b, v87
	v_pk_mul_f32 v[116:117], v[116:117], v[116:117]
	v_exp_f32_e32 v86, v86
	v_exp_f32_e32 v87, v87
	v_add_f32_e32 v96, 1.0, v96
	v_add_f32_e32 v97, 1.0, v97
	v_pk_mul_f32 v[118:119], v[118:119], v[118:119]
	v_sub_f32_e32 v116, 1.0, v116
	v_sub_f32_e32 v117, 1.0, v117
	v_rcp_f32_e32 v96, v96
	v_rcp_f32_e32 v97, v97
	v_add_f32_e32 v98, 1.0, v98
	v_add_f32_e32 v99, 1.0, v99
	v_sqrt_f32_e32 v116, v116
	v_sub_f32_e32 v118, 1.0, v118
	v_sub_f32_e32 v119, 1.0, v119
	v_sqrt_f32_e32 v117, v117
	v_rcp_f32_e32 v98, v98
	v_rcp_f32_e32 v99, v99
	v_sqrt_f32_e32 v118, v118
	v_sqrt_f32_e32 v119, v119
	v_add_f32_e32 v84, 1.0, v84
	v_add_f32_e32 v85, 1.0, v85
	v_rcp_f32_e32 v84, v84
	v_rcp_f32_e32 v85, v85
	v_add_f32_e32 v86, 1.0, v86
	v_add_f32_e32 v87, 1.0, v87
	v_rcp_f32_e32 v86, v86
	v_rcp_f32_e32 v87, v87
	global_store_dwordx4 v[124:125], v[112:115], off offset:16
	v_pk_mul_f32 v[96:97], v[96:97], v[116:117]
	v_lshlrev_b32_e32 v120, 16, v165
	v_lshlrev_b32_e32 v114, 16, v164
	v_and_b32_e32 v115, 0xffff0000, v164
	v_lshlrev_b64 v[112:113], 13, v[206:207]
	v_and_b32_e32 v121, 0xffff0000, v165
	v_pk_mul_f32 v[98:99], v[98:99], v[118:119]
	v_pk_mul_f32 v[96:97], v[96:97], v[114:115]
	v_pk_mul_f32 v[98:99], v[98:99], v[120:121]
	v_cvt_pk_bf16_f32 v96, v104, v96
	v_cvt_pk_bf16_f32 v97, v105, v97
	v_lshl_add_u64 v[104:105], s[92:93], 0, v[112:113]
	v_pk_mul_f32 v[84:85], v[64:65], v[84:85]
	v_cvt_pk_bf16_f32 v98, v106, v98
	v_cvt_pk_bf16_f32 v99, v107, v99
	v_lshl_add_u64 v[104:105], v[104:105], 0, v[196:197]
	v_pk_add_f32 v[76:77], v[76:77], v[72:73]
	v_pk_mul_f32 v[86:87], v[66:67], v[86:87]
	v_pk_mul_f32 v[84:85], v[84:85], s[62:63] op_sel_hi:[1,0]
	v_pk_add_f32 v[60:61], v[60:61], v[100:101]
	global_store_dwordx4 v[104:105], v[96:99], off
	v_pk_add_f32 v[78:79], v[78:79], v[74:75]
	v_mul_f32_e32 v76, 0xbfb8aa3b, v76
	v_mul_f32_e32 v77, 0xbfb8aa3b, v77
	v_pk_mul_f32 v[86:87], v[86:87], s[62:63] op_sel_hi:[1,0]
	v_exp_f32_e32 v98, v84
	v_exp_f32_e32 v99, v85
	v_pk_add_f32 v[62:63], v[62:63], v[102:103]
	v_mul_f32_e32 v60, 0xbfb8aa3b, v60
	v_mul_f32_e32 v61, 0xbfb8aa3b, v61
	v_exp_f32_e32 v76, v76
	v_exp_f32_e32 v77, v77
	v_mul_f32_e32 v78, 0xbfb8aa3b, v78
	v_mul_f32_e32 v79, 0xbfb8aa3b, v79
	v_exp_f32_e32 v106, v86
	v_exp_f32_e32 v107, v87
	v_exp_f32_e32 v60, v60
	v_exp_f32_e32 v61, v61
	v_mul_f32_e32 v62, 0xbfb8aa3b, v62
	v_mul_f32_e32 v63, 0xbfb8aa3b, v63
	v_exp_f32_e32 v78, v78
	v_exp_f32_e32 v79, v79
	v_exp_f32_e32 v62, v62
	v_exp_f32_e32 v63, v63
	v_pk_mul_f32 v[98:99], v[98:99], v[98:99]
	v_add_f32_e32 v76, 1.0, v76
	v_add_f32_e32 v77, 1.0, v77
	v_pk_mul_f32 v[106:107], v[106:107], v[106:107]
	v_sub_f32_e32 v98, 1.0, v98
	v_sub_f32_e32 v99, 1.0, v99
	v_add_f32_e32 v60, 1.0, v60
	v_add_f32_e32 v61, 1.0, v61
	v_rcp_f32_e32 v76, v76
	v_rcp_f32_e32 v77, v77
	v_add_f32_e32 v78, 1.0, v78
	v_add_f32_e32 v79, 1.0, v79
	v_sqrt_f32_e32 v98, v98
	v_sub_f32_e32 v106, 1.0, v106
	v_sub_f32_e32 v107, 1.0, v107
	v_sqrt_f32_e32 v99, v99
	v_rcp_f32_e32 v60, v60
	v_rcp_f32_e32 v61, v61
	v_add_f32_e32 v62, 1.0, v62
	v_add_f32_e32 v63, 1.0, v63
	v_rcp_f32_e32 v78, v78
	v_rcp_f32_e32 v79, v79
	v_sqrt_f32_e32 v106, v106
	v_sqrt_f32_e32 v107, v107
	v_rcp_f32_e32 v62, v62
	v_rcp_f32_e32 v63, v63
	v_lshlrev_b32_e32 v96, 16, v166
	v_and_b32_e32 v97, 0xffff0000, v166
	v_pk_mul_f32 v[76:77], v[76:77], v[98:99]
	v_pk_mul_f32 v[60:61], v[88:89], v[60:61]
	v_lshlrev_b32_e32 v112, 16, v167
	v_and_b32_e32 v113, 0xffff0000, v167
	v_pk_mul_f32 v[78:79], v[78:79], v[106:107]
	v_pk_mul_f32 v[76:77], v[76:77], v[96:97]
	v_pk_add_f32 v[56:57], v[56:57], v[92:93]
	v_pk_mul_f32 v[62:63], v[90:91], v[62:63]
; __device__ __forceinline__ unsigned cvt_pk_bf16(float lo, float hi) { unsigned r; asm volatile("v_cvt_pk_bf16_f32 %0, %1, %2" : "=v"(r) : "v"(lo), "v"(hi)); return r; }
; __device__ __forceinline__ float bf_lo(unsigned w) { return __uint_as_float(w << 16); }
; __device__ __forceinline__ float bf_hi(unsigned w) { return __uint_as_float(w & 0xffff0000u); }
;     __device__ __forceinline__ void operator()(EPI_ARGS) const {
;     ...
; #pragma unroll
;         for (int ai = 0; ai < 2; ++ai)
; #pragma unroll
;             for (int m = 0; m < 4; ++m) {
;                 const int row = ROW_OF(ai, m);
; #pragma unroll
;                 for (int n = 0; n < 2; ++n) {
;                     const unsigned w0 = n ? vv[ai][m].z : vv[ai][m].x, w1 = n ? vv[ai][m].w : vv[ai][m].y;
;                     const f32x4 vx = (f32x4){bf_lo(w0), bf_hi(w0), bf_lo(w1), bf_hi(w1)};
;                     const f32x4 r = sigmoid4(acc[ai][0][m][n] + ba[n]), ig = sigmoid4(acc[ai][1][m][n] + bi[n]);
;                     const f32x4 la = sp[n] * r * (-1.4426950409f);
;                     f32x4 av;
; #pragma unroll
;                     for (int j = 0; j < 4; ++j) av[j] = __builtin_amdgcn_exp2f(la[j]);
;                     const f32x4 om = 1.0f - av * av; f32x4 sq;
; #pragma unroll
;                     for (int j = 0; j < 4; ++j) sq[j] = __builtin_amdgcn_sqrtf(om[j]);
;                     const f32x4 bx = sq * ig * vx;
;                     u32x4 w; w.x = cvt_pk_bf16(la[0], bx[0]); w.y = cvt_pk_bf16(la[1], bx[1]); w.z = cvt_pk_bf16(la[2], bx[2]); w.w = cvt_pk_bf16(la[3], bx[3]);
;                     *(u32x4*)(AB + (size_t)row * LW + c0 + 4 * n) = w;
	v_pk_mul_f32 v[60:61], v[60:61], s[62:63] op_sel_hi:[1,0]
	v_pk_mul_f32 v[78:79], v[78:79], v[112:113]
	v_cvt_pk_bf16_f32 v76, v84, v76
	v_cvt_pk_bf16_f32 v77, v85, v77
	v_pk_add_f32 v[58:59], v[58:59], v[94:95]
	v_mul_f32_e32 v56, 0xbfb8aa3b, v56
	v_mul_f32_e32 v57, 0xbfb8aa3b, v57
	v_pk_mul_f32 v[62:63], v[62:63], s[62:63] op_sel_hi:[1,0]
	v_exp_f32_e32 v84, v60
	v_exp_f32_e32 v85, v61
	v_cvt_pk_bf16_f32 v78, v86, v78
	v_cvt_pk_bf16_f32 v79, v87, v79
	v_exp_f32_e32 v56, v56
	v_exp_f32_e32 v57, v57
	v_mul_f32_e32 v58, 0xbfb8aa3b, v58
	v_mul_f32_e32 v59, 0xbfb8aa3b, v59
	v_exp_f32_e32 v86, v62
	v_exp_f32_e32 v87, v63
	v_pk_add_f32 v[52:53], v[52:53], v[80:81]
	v_exp_f32_e32 v58, v58
	v_exp_f32_e32 v59, v59
	v_pk_add_f32 v[54:55], v[54:55], v[82:83]
	v_mul_f32_e32 v52, 0xbfb8aa3b, v52
	v_mul_f32_e32 v53, 0xbfb8aa3b, v53
	v_exp_f32_e32 v52, v52
	v_exp_f32_e32 v53, v53
	v_mul_f32_e32 v54, 0xbfb8aa3b, v54
	v_mul_f32_e32 v55, 0xbfb8aa3b, v55
	v_pk_mul_f32 v[84:85], v[84:85], v[84:85]
	v_exp_f32_e32 v54, v54
	v_exp_f32_e32 v55, v55
	v_add_f32_e32 v56, 1.0, v56
	v_add_f32_e32 v57, 1.0, v57
	v_pk_mul_f32 v[86:87], v[86:87], v[86:87]
	v_sub_f32_e32 v84, 1.0, v84
	v_sub_f32_e32 v85, 1.0, v85
	v_rcp_f32_e32 v56, v56
	v_rcp_f32_e32 v57, v57
	v_add_f32_e32 v58, 1.0, v58
	v_add_f32_e32 v59, 1.0, v59
	v_sqrt_f32_e32 v84, v84
	v_sub_f32_e32 v86, 1.0, v86
	v_sub_f32_e32 v87, 1.0, v87
	v_sqrt_f32_e32 v85, v85
	v_rcp_f32_e32 v58, v58
	v_rcp_f32_e32 v59, v59
	v_sqrt_f32_e32 v86, v86
	v_sqrt_f32_e32 v87, v87
	v_add_f32_e32 v52, 1.0, v52
	v_add_f32_e32 v53, 1.0, v53
	v_rcp_f32_e32 v52, v52
	v_rcp_f32_e32 v53, v53
	v_add_f32_e32 v54, 1.0, v54
	v_add_f32_e32 v55, 1.0, v55
	v_rcp_f32_e32 v54, v54
	v_rcp_f32_e32 v55, v55
	global_store_dwordx4 v[104:105], v[76:79], off offset:16
	v_pk_mul_f32 v[56:57], v[56:57], v[84:85]
	v_lshlrev_b32_e32 v96, 16, v149
	v_lshlrev_b32_e32 v78, 16, v148
	v_and_b32_e32 v79, 0xffff0000, v148
	v_lshlrev_b64 v[76:77], 13, v[204:205]
	v_and_b32_e32 v97, 0xffff0000, v149
	v_pk_mul_f32 v[58:59], v[58:59], v[86:87]
	v_pk_mul_f32 v[56:57], v[56:57], v[78:79]
	v_pk_mul_f32 v[58:59], v[58:59], v[96:97]
	v_cvt_pk_bf16_f32 v56, v60, v56
	v_cvt_pk_bf16_f32 v57, v61, v57
	v_lshl_add_u64 v[60:61], s[92:93], 0, v[76:77]
	v_pk_mul_f32 v[52:53], v[64:65], v[52:53]
	v_cvt_pk_bf16_f32 v58, v62, v58
	v_cvt_pk_bf16_f32 v59, v63, v59
	v_lshl_add_u64 v[60:61], v[60:61], 0, v[196:197]
	v_pk_add_f32 v[48:49], v[48:49], v[72:73]
	v_pk_mul_f32 v[54:55], v[66:67], v[54:55]
	v_pk_mul_f32 v[52:53], v[52:53], s[62:63] op_sel_hi:[1,0]
	v_pk_add_f32 v[44:45], v[44:45], v[100:101]
	global_store_dwordx4 v[60:61], v[56:59], off
	v_pk_add_f32 v[50:51], v[50:51], v[74:75]
	v_mul_f32_e32 v48, 0xbfb8aa3b, v48
	v_mul_f32_e32 v49, 0xbfb8aa3b, v49
	v_pk_mul_f32 v[54:55], v[54:55], s[62:63] op_sel_hi:[1,0]
	v_exp_f32_e32 v58, v52
	v_exp_f32_e32 v59, v53
	v_pk_add_f32 v[46:47], v[46:47], v[102:103]
	v_mul_f32_e32 v44, 0xbfb8aa3b, v44
	v_mul_f32_e32 v45, 0xbfb8aa3b, v45
	v_exp_f32_e32 v48, v48
	v_exp_f32_e32 v49, v49
	v_mul_f32_e32 v50, 0xbfb8aa3b, v50
	v_mul_f32_e32 v51, 0xbfb8aa3b, v51
	v_exp_f32_e32 v62, v54
	v_exp_f32_e32 v63, v55
	v_exp_f32_e32 v44, v44
	v_exp_f32_e32 v45, v45
	v_mul_f32_e32 v46, 0xbfb8aa3b, v46
	v_mul_f32_e32 v47, 0xbfb8aa3b, v47
	v_exp_f32_e32 v50, v50
	v_exp_f32_e32 v51, v51
	v_exp_f32_e32 v46, v46
	v_exp_f32_e32 v47, v47
	v_pk_mul_f32 v[58:59], v[58:59], v[58:59]
	v_add_f32_e32 v48, 1.0, v48
	v_add_f32_e32 v49, 1.0, v49
	v_pk_mul_f32 v[62:63], v[62:63], v[62:63]
	v_sub_f32_e32 v58, 1.0, v58
	v_sub_f32_e32 v59, 1.0, v59
	v_add_f32_e32 v44, 1.0, v44
	v_add_f32_e32 v45, 1.0, v45
	v_rcp_f32_e32 v48, v48
	v_rcp_f32_e32 v49, v49
	v_add_f32_e32 v50, 1.0, v50
	v_add_f32_e32 v51, 1.0, v51
	v_sqrt_f32_e32 v58, v58
	v_sub_f32_e32 v62, 1.0, v62
	v_sub_f32_e32 v63, 1.0, v63
	v_sqrt_f32_e32 v59, v59
	v_rcp_f32_e32 v44, v44
	v_rcp_f32_e32 v45, v45
	v_add_f32_e32 v46, 1.0, v46
	v_add_f32_e32 v47, 1.0, v47
	v_rcp_f32_e32 v50, v50
	v_rcp_f32_e32 v51, v51
	v_sqrt_f32_e32 v62, v62
	v_sqrt_f32_e32 v63, v63
	v_rcp_f32_e32 v46, v46
	v_rcp_f32_e32 v47, v47
	v_lshlrev_b32_e32 v56, 16, v150
	v_and_b32_e32 v57, 0xffff0000, v150
	v_pk_mul_f32 v[48:49], v[48:49], v[58:59]
	v_pk_mul_f32 v[44:45], v[88:89], v[44:45]
	v_lshlrev_b32_e32 v76, 16, v151
	v_and_b32_e32 v77, 0xffff0000, v151
	v_pk_mul_f32 v[50:51], v[50:51], v[62:63]
	v_pk_mul_f32 v[48:49], v[48:49], v[56:57]
	v_pk_add_f32 v[40:41], v[40:41], v[92:93]
	v_pk_mul_f32 v[46:47], v[90:91], v[46:47]
	v_pk_mul_f32 v[44:45], v[44:45], s[62:63] op_sel_hi:[1,0]
	v_pk_mul_f32 v[50:51], v[50:51], v[76:77]
	v_cvt_pk_bf16_f32 v48, v52, v48
	v_cvt_pk_bf16_f32 v49, v53, v49
	v_pk_add_f32 v[42:43], v[42:43], v[94:95]
	v_mul_f32_e32 v40, 0xbfb8aa3b, v40
	v_mul_f32_e32 v41, 0xbfb8aa3b, v41
	v_pk_mul_f32 v[46:47], v[46:47], s[62:63] op_sel_hi:[1,0]
	v_exp_f32_e32 v52, v44
	v_exp_f32_e32 v53, v45
	v_cvt_pk_bf16_f32 v50, v54, v50
	v_cvt_pk_bf16_f32 v51, v55, v51
	v_exp_f32_e32 v40, v40
	v_exp_f32_e32 v41, v41
	v_mul_f32_e32 v42, 0xbfb8aa3b, v42
	v_mul_f32_e32 v43, 0xbfb8aa3b, v43
	v_exp_f32_e32 v54, v46
	v_exp_f32_e32 v55, v47
	v_pk_add_f32 v[36:37], v[36:37], v[80:81]
	v_exp_f32_e32 v42, v42
	v_exp_f32_e32 v43, v43
	v_pk_add_f32 v[38:39], v[38:39], v[82:83]
	v_mul_f32_e32 v36, 0xbfb8aa3b, v36
	v_mul_f32_e32 v37, 0xbfb8aa3b, v37
	v_exp_f32_e32 v36, v36
	v_exp_f32_e32 v37, v37
	v_mul_f32_e32 v38, 0xbfb8aa3b, v38
	v_mul_f32_e32 v39, 0xbfb8aa3b, v39
	v_pk_mul_f32 v[52:53], v[52:53], v[52:53]
	v_exp_f32_e32 v38, v38
	v_exp_f32_e32 v39, v39
	v_add_f32_e32 v40, 1.0, v40
	v_add_f32_e32 v41, 1.0, v41
	v_pk_mul_f32 v[54:55], v[54:55], v[54:55]
; __device__ __forceinline__ unsigned cvt_pk_bf16(float lo, float hi) { unsigned r; asm volatile("v_cvt_pk_bf16_f32 %0, %1, %2" : "=v"(r) : "v"(lo), "v"(hi)); return r; }
; __device__ __forceinline__ float bf_lo(unsigned w) { return __uint_as_float(w << 16); }
; __device__ __forceinline__ float bf_hi(unsigned w) { return __uint_as_float(w & 0xffff0000u); }
;     __device__ __forceinline__ void operator()(EPI_ARGS) const {
;     ...
; #pragma unroll
;         for (int ai = 0; ai < 2; ++ai)
; #pragma unroll
;             for (int m = 0; m < 4; ++m) {
;                 const int row = ROW_OF(ai, m);
; #pragma unroll
;                 for (int n = 0; n < 2; ++n) {
;                     const unsigned w0 = n ? vv[ai][m].z : vv[ai][m].x, w1 = n ? vv[ai][m].w : vv[ai][m].y;
;                     const f32x4 vx = (f32x4){bf_lo(w0), bf_hi(w0), bf_lo(w1), bf_hi(w1)};
;                     const f32x4 r = sigmoid4(acc[ai][0][m][n] + ba[n]), ig = sigmoid4(acc[ai][1][m][n] + bi[n]);
;                     const f32x4 la = sp[n] * r * (-1.4426950409f);
;                     f32x4 av;
; #pragma unroll
;                     for (int j = 0; j < 4; ++j) av[j] = __builtin_amdgcn_exp2f(la[j]);
;                     const f32x4 om = 1.0f - av * av; f32x4 sq;
; #pragma unroll
;                     for (int j = 0; j < 4; ++j) sq[j] = __builtin_amdgcn_sqrtf(om[j]);
;                     const f32x4 bx = sq * ig * vx;
;                     u32x4 w; w.x = cvt_pk_bf16(la[0], bx[0]); w.y = cvt_pk_bf16(la[1], bx[1]); w.z = cvt_pk_bf16(la[2], bx[2]); w.w = cvt_pk_bf16(la[3], bx[3]);
;                     *(u32x4*)(AB + (size_t)row * LW + c0 + 4 * n) = w;
	v_sub_f32_e32 v52, 1.0, v52
	v_sub_f32_e32 v53, 1.0, v53
	v_rcp_f32_e32 v40, v40
	v_rcp_f32_e32 v41, v41
	v_add_f32_e32 v42, 1.0, v42
	v_add_f32_e32 v43, 1.0, v43
	v_sqrt_f32_e32 v52, v52
	v_sub_f32_e32 v54, 1.0, v54
	v_sub_f32_e32 v55, 1.0, v55
	v_sqrt_f32_e32 v53, v53
	v_rcp_f32_e32 v42, v42
	v_rcp_f32_e32 v43, v43
	v_sqrt_f32_e32 v54, v54
	v_sqrt_f32_e32 v55, v55
	v_add_f32_e32 v36, 1.0, v36
	v_add_f32_e32 v37, 1.0, v37
	v_rcp_f32_e32 v36, v36
	v_rcp_f32_e32 v37, v37
	v_add_f32_e32 v38, 1.0, v38
	v_add_f32_e32 v39, 1.0, v39
	v_rcp_f32_e32 v38, v38
	v_rcp_f32_e32 v39, v39
	global_store_dwordx4 v[60:61], v[48:51], off offset:16
	v_pk_mul_f32 v[40:41], v[40:41], v[52:53]
	v_lshlrev_b32_e32 v56, 16, v129
	v_lshlrev_b32_e32 v50, 16, v128
	v_and_b32_e32 v51, 0xffff0000, v128
	v_lshlrev_b64 v[48:49], 13, v[202:203]
	v_and_b32_e32 v57, 0xffff0000, v129
	v_pk_mul_f32 v[42:43], v[42:43], v[54:55]
	v_pk_mul_f32 v[40:41], v[40:41], v[50:51]
	v_pk_mul_f32 v[42:43], v[42:43], v[56:57]
	v_cvt_pk_bf16_f32 v40, v44, v40
	v_cvt_pk_bf16_f32 v41, v45, v41
	v_lshl_add_u64 v[44:45], s[92:93], 0, v[48:49]
	v_pk_mul_f32 v[36:37], v[64:65], v[36:37]
	v_cvt_pk_bf16_f32 v42, v46, v42
	v_cvt_pk_bf16_f32 v43, v47, v43
	v_lshl_add_u64 v[44:45], v[44:45], 0, v[196:197]
	v_pk_add_f32 v[32:33], v[32:33], v[72:73]
	v_pk_mul_f32 v[38:39], v[66:67], v[38:39]
	v_pk_mul_f32 v[36:37], v[36:37], s[62:63] op_sel_hi:[1,0]
	v_pk_add_f32 v[28:29], v[28:29], v[100:101]
	global_store_dwordx4 v[44:45], v[40:43], off
	v_pk_add_f32 v[34:35], v[34:35], v[74:75]
	v_mul_f32_e32 v32, 0xbfb8aa3b, v32
	v_mul_f32_e32 v33, 0xbfb8aa3b, v33
	v_pk_mul_f32 v[38:39], v[38:39], s[62:63] op_sel_hi:[1,0]
	v_exp_f32_e32 v42, v36
	v_exp_f32_e32 v43, v37
	v_pk_add_f32 v[30:31], v[30:31], v[102:103]
	v_mul_f32_e32 v28, 0xbfb8aa3b, v28
	v_mul_f32_e32 v29, 0xbfb8aa3b, v29
	v_exp_f32_e32 v32, v32
	v_exp_f32_e32 v33, v33
	v_mul_f32_e32 v34, 0xbfb8aa3b, v34
	v_mul_f32_e32 v35, 0xbfb8aa3b, v35
	v_exp_f32_e32 v46, v38
	v_exp_f32_e32 v47, v39
	v_exp_f32_e32 v28, v28
	v_exp_f32_e32 v29, v29
	v_mul_f32_e32 v30, 0xbfb8aa3b, v30
	v_mul_f32_e32 v31, 0xbfb8aa3b, v31
	v_exp_f32_e32 v34, v34
	v_exp_f32_e32 v35, v35
	v_exp_f32_e32 v30, v30
	v_exp_f32_e32 v31, v31
	v_pk_mul_f32 v[42:43], v[42:43], v[42:43]
	v_add_f32_e32 v32, 1.0, v32
	v_add_f32_e32 v33, 1.0, v33
	v_pk_mul_f32 v[46:47], v[46:47], v[46:47]
	v_sub_f32_e32 v42, 1.0, v42
	v_sub_f32_e32 v43, 1.0, v43
	v_add_f32_e32 v28, 1.0, v28
	v_add_f32_e32 v29, 1.0, v29
	v_rcp_f32_e32 v32, v32
	v_rcp_f32_e32 v33, v33
	v_add_f32_e32 v34, 1.0, v34
	v_add_f32_e32 v35, 1.0, v35
	v_sqrt_f32_e32 v42, v42
	v_sub_f32_e32 v46, 1.0, v46
	v_sub_f32_e32 v47, 1.0, v47
	v_sqrt_f32_e32 v43, v43
	v_rcp_f32_e32 v28, v28
	v_rcp_f32_e32 v29, v29
	v_add_f32_e32 v30, 1.0, v30
	v_add_f32_e32 v31, 1.0, v31
	v_rcp_f32_e32 v34, v34
	v_rcp_f32_e32 v35, v35
	v_sqrt_f32_e32 v46, v46
	v_sqrt_f32_e32 v47, v47
	v_rcp_f32_e32 v30, v30
	v_rcp_f32_e32 v31, v31
	v_lshlrev_b32_e32 v40, 16, v130
	v_and_b32_e32 v41, 0xffff0000, v130
	v_pk_mul_f32 v[32:33], v[32:33], v[42:43]
	v_pk_mul_f32 v[28:29], v[88:89], v[28:29]
	v_lshlrev_b32_e32 v48, 16, v131
	v_and_b32_e32 v49, 0xffff0000, v131
	v_pk_mul_f32 v[34:35], v[34:35], v[46:47]
	v_pk_mul_f32 v[32:33], v[32:33], v[40:41]
	v_pk_add_f32 v[24:25], v[24:25], v[92:93]
	v_pk_mul_f32 v[30:31], v[90:91], v[30:31]
	v_pk_mul_f32 v[28:29], v[28:29], s[62:63] op_sel_hi:[1,0]
	v_pk_mul_f32 v[34:35], v[34:35], v[48:49]
	v_cvt_pk_bf16_f32 v32, v36, v32
	v_cvt_pk_bf16_f32 v33, v37, v33
	v_pk_add_f32 v[26:27], v[26:27], v[94:95]
	v_mul_f32_e32 v24, 0xbfb8aa3b, v24
	v_mul_f32_e32 v25, 0xbfb8aa3b, v25
	v_pk_mul_f32 v[30:31], v[30:31], s[62:63] op_sel_hi:[1,0]
	v_exp_f32_e32 v36, v28
	v_exp_f32_e32 v37, v29
	v_cvt_pk_bf16_f32 v34, v38, v34
	v_cvt_pk_bf16_f32 v35, v39, v35
	v_exp_f32_e32 v24, v24
	v_exp_f32_e32 v25, v25
	v_mul_f32_e32 v26, 0xbfb8aa3b, v26
	v_mul_f32_e32 v27, 0xbfb8aa3b, v27
	v_exp_f32_e32 v38, v30
	v_exp_f32_e32 v39, v31
	v_pk_add_f32 v[20:21], v[20:21], v[80:81]
	v_exp_f32_e32 v26, v26
	v_exp_f32_e32 v27, v27
	v_pk_add_f32 v[22:23], v[22:23], v[82:83]
	v_mul_f32_e32 v20, 0xbfb8aa3b, v20
	v_mul_f32_e32 v21, 0xbfb8aa3b, v21
	v_exp_f32_e32 v20, v20
	v_exp_f32_e32 v21, v21
	v_mul_f32_e32 v22, 0xbfb8aa3b, v22
	v_mul_f32_e32 v23, 0xbfb8aa3b, v23
	v_pk_mul_f32 v[36:37], v[36:37], v[36:37]
	v_exp_f32_e32 v22, v22
	v_exp_f32_e32 v23, v23
	v_add_f32_e32 v24, 1.0, v24
	v_add_f32_e32 v25, 1.0, v25
	v_pk_mul_f32 v[38:39], v[38:39], v[38:39]
	v_sub_f32_e32 v36, 1.0, v36
	v_sub_f32_e32 v37, 1.0, v37
	v_rcp_f32_e32 v24, v24
	v_rcp_f32_e32 v25, v25
	v_add_f32_e32 v26, 1.0, v26
	v_add_f32_e32 v27, 1.0, v27
	v_sqrt_f32_e32 v36, v36
	v_sub_f32_e32 v38, 1.0, v38
	v_sub_f32_e32 v39, 1.0, v39
	v_sqrt_f32_e32 v37, v37
	v_rcp_f32_e32 v26, v26
	v_rcp_f32_e32 v27, v27
	v_sqrt_f32_e32 v38, v38
	v_sqrt_f32_e32 v39, v39
	v_add_f32_e32 v20, 1.0, v20
	v_add_f32_e32 v21, 1.0, v21
	v_rcp_f32_e32 v20, v20
	v_rcp_f32_e32 v21, v21
	v_add_f32_e32 v22, 1.0, v22
	v_add_f32_e32 v23, 1.0, v23
	v_rcp_f32_e32 v22, v22
	v_rcp_f32_e32 v23, v23
	global_store_dwordx4 v[44:45], v[32:35], off offset:16
	v_pk_mul_f32 v[24:25], v[24:25], v[36:37]
	v_lshlrev_b32_e32 v40, 16, v109
	v_lshlrev_b32_e32 v34, 16, v108
	v_and_b32_e32 v35, 0xffff0000, v108
	v_lshlrev_b64 v[32:33], 13, v[200:201]
	v_and_b32_e32 v41, 0xffff0000, v109
	v_pk_mul_f32 v[26:27], v[26:27], v[38:39]
	v_pk_mul_f32 v[24:25], v[24:25], v[34:35]
	v_pk_mul_f32 v[26:27], v[26:27], v[40:41]
	v_cvt_pk_bf16_f32 v24, v28, v24
	v_cvt_pk_bf16_f32 v25, v29, v25
	v_lshl_add_u64 v[28:29], s[92:93], 0, v[32:33]
	v_pk_mul_f32 v[20:21], v[64:65], v[20:21]
; __device__ __forceinline__ unsigned cvt_pk_bf16(float lo, float hi) { unsigned r; asm volatile("v_cvt_pk_bf16_f32 %0, %1, %2" : "=v"(r) : "v"(lo), "v"(hi)); return r; }
; __device__ __forceinline__ float bf_lo(unsigned w) { return __uint_as_float(w << 16); }
; __device__ __forceinline__ float bf_hi(unsigned w) { return __uint_as_float(w & 0xffff0000u); }
;     __device__ __forceinline__ void operator()(EPI_ARGS) const {
;     ...
; #pragma unroll
;         for (int ai = 0; ai < 2; ++ai)
; #pragma unroll
;             for (int m = 0; m < 4; ++m) {
;                 const int row = ROW_OF(ai, m);
; #pragma unroll
;                 for (int n = 0; n < 2; ++n) {
;                     const unsigned w0 = n ? vv[ai][m].z : vv[ai][m].x, w1 = n ? vv[ai][m].w : vv[ai][m].y;
;                     const f32x4 vx = (f32x4){bf_lo(w0), bf_hi(w0), bf_lo(w1), bf_hi(w1)};
;                     const f32x4 r = sigmoid4(acc[ai][0][m][n] + ba[n]), ig = sigmoid4(acc[ai][1][m][n] + bi[n]);
;                     const f32x4 la = sp[n] * r * (-1.4426950409f);
;                     f32x4 av;
; #pragma unroll
;                     for (int j = 0; j < 4; ++j) av[j] = __builtin_amdgcn_exp2f(la[j]);
;                     const f32x4 om = 1.0f - av * av; f32x4 sq;
; #pragma unroll
;                     for (int j = 0; j < 4; ++j) sq[j] = __builtin_amdgcn_sqrtf(om[j]);
;                     const f32x4 bx = sq * ig * vx;
;                     u32x4 w; w.x = cvt_pk_bf16(la[0], bx[0]); w.y = cvt_pk_bf16(la[1], bx[1]); w.z = cvt_pk_bf16(la[2], bx[2]); w.w = cvt_pk_bf16(la[3], bx[3]);
;                     *(u32x4*)(AB + (size_t)row * LW + c0 + 4 * n) = w;
;     __device__ __forceinline__ void operator()(f32x4 (&acc)[2][2][4][2], const Unit& u, int wr, int wc, int fr, int fq) const {
;     ...
;         asm volatile("s_waitcnt vmcnt(0)" ::: "memory"); __builtin_amdgcn_s_barrier();
	v_cvt_pk_bf16_f32 v26, v30, v26
	v_cvt_pk_bf16_f32 v27, v31, v27
	v_lshl_add_u64 v[28:29], v[28:29], 0, v[196:197]
	v_pk_add_f32 v[16:17], v[16:17], v[72:73]
	v_pk_mul_f32 v[22:23], v[66:67], v[22:23]
	v_pk_mul_f32 v[20:21], v[20:21], s[62:63] op_sel_hi:[1,0]
	v_pk_add_f32 v[12:13], v[12:13], v[100:101]
	global_store_dwordx4 v[28:29], v[24:27], off
	v_pk_add_f32 v[18:19], v[18:19], v[74:75]
	v_mul_f32_e32 v16, 0xbfb8aa3b, v16
	v_mul_f32_e32 v17, 0xbfb8aa3b, v17
	v_pk_mul_f32 v[22:23], v[22:23], s[62:63] op_sel_hi:[1,0]
	v_exp_f32_e32 v26, v20
	v_exp_f32_e32 v27, v21
	v_pk_add_f32 v[14:15], v[14:15], v[102:103]
	v_mul_f32_e32 v12, 0xbfb8aa3b, v12
	v_mul_f32_e32 v13, 0xbfb8aa3b, v13
	v_exp_f32_e32 v16, v16
	v_exp_f32_e32 v17, v17
	v_mul_f32_e32 v18, 0xbfb8aa3b, v18
	v_mul_f32_e32 v19, 0xbfb8aa3b, v19
	v_exp_f32_e32 v30, v22
	v_exp_f32_e32 v31, v23
	v_exp_f32_e32 v12, v12
	v_exp_f32_e32 v13, v13
	v_mul_f32_e32 v14, 0xbfb8aa3b, v14
	v_mul_f32_e32 v15, 0xbfb8aa3b, v15
	v_exp_f32_e32 v18, v18
	v_exp_f32_e32 v19, v19
	v_exp_f32_e32 v14, v14
	v_exp_f32_e32 v15, v15
	v_pk_mul_f32 v[26:27], v[26:27], v[26:27]
	v_add_f32_e32 v16, 1.0, v16
	v_add_f32_e32 v17, 1.0, v17
	v_pk_mul_f32 v[30:31], v[30:31], v[30:31]
	v_sub_f32_e32 v26, 1.0, v26
	v_sub_f32_e32 v27, 1.0, v27
	v_add_f32_e32 v12, 1.0, v12
	v_add_f32_e32 v13, 1.0, v13
	v_rcp_f32_e32 v16, v16
	v_rcp_f32_e32 v17, v17
	v_add_f32_e32 v18, 1.0, v18
	v_add_f32_e32 v19, 1.0, v19
	v_sqrt_f32_e32 v26, v26
	v_sub_f32_e32 v30, 1.0, v30
	v_sub_f32_e32 v31, 1.0, v31
	v_sqrt_f32_e32 v27, v27
	v_rcp_f32_e32 v12, v12
	v_rcp_f32_e32 v13, v13
	v_add_f32_e32 v14, 1.0, v14
	v_add_f32_e32 v15, 1.0, v15
	v_rcp_f32_e32 v18, v18
	v_rcp_f32_e32 v19, v19
	v_sqrt_f32_e32 v30, v30
	v_sqrt_f32_e32 v31, v31
	v_rcp_f32_e32 v14, v14
	v_rcp_f32_e32 v15, v15
	v_lshlrev_b32_e32 v24, 16, v110
	v_and_b32_e32 v25, 0xffff0000, v110
	v_pk_mul_f32 v[16:17], v[16:17], v[26:27]
	v_pk_mul_f32 v[12:13], v[88:89], v[12:13]
	v_lshlrev_b32_e32 v32, 16, v111
	v_and_b32_e32 v33, 0xffff0000, v111
	v_pk_mul_f32 v[18:19], v[18:19], v[30:31]
	v_pk_mul_f32 v[16:17], v[16:17], v[24:25]
	v_pk_add_f32 v[8:9], v[8:9], v[92:93]
	v_pk_mul_f32 v[14:15], v[90:91], v[14:15]
	v_pk_mul_f32 v[12:13], v[12:13], s[62:63] op_sel_hi:[1,0]
	v_pk_mul_f32 v[18:19], v[18:19], v[32:33]
	v_cvt_pk_bf16_f32 v16, v20, v16
	v_cvt_pk_bf16_f32 v17, v21, v17
	v_pk_add_f32 v[10:11], v[10:11], v[94:95]
	v_mul_f32_e32 v8, 0xbfb8aa3b, v8
	v_mul_f32_e32 v9, 0xbfb8aa3b, v9
	v_pk_mul_f32 v[14:15], v[14:15], s[62:63] op_sel_hi:[1,0]
	v_exp_f32_e32 v20, v12
	v_exp_f32_e32 v21, v13
	v_cvt_pk_bf16_f32 v18, v22, v18
	v_cvt_pk_bf16_f32 v19, v23, v19
	v_exp_f32_e32 v8, v8
	v_exp_f32_e32 v9, v9
	v_mul_f32_e32 v10, 0xbfb8aa3b, v10
	v_mul_f32_e32 v11, 0xbfb8aa3b, v11
	v_exp_f32_e32 v22, v14
	v_exp_f32_e32 v23, v15
	v_pk_add_f32 v[6:7], v[6:7], v[82:83]
	v_pk_add_f32 v[4:5], v[4:5], v[80:81]
	v_exp_f32_e32 v10, v10
	v_exp_f32_e32 v11, v11
	v_mul_f32_e32 v4, 0xbfb8aa3b, v4
	v_mul_f32_e32 v5, 0xbfb8aa3b, v5
	v_mul_f32_e32 v6, 0xbfb8aa3b, v6
	v_mul_f32_e32 v7, 0xbfb8aa3b, v7
	v_exp_f32_e32 v4, v4
	v_exp_f32_e32 v5, v5
	v_exp_f32_e32 v6, v6
	v_exp_f32_e32 v7, v7
	v_pk_mul_f32 v[20:21], v[20:21], v[20:21]
	v_add_f32_e32 v8, 1.0, v8
	v_add_f32_e32 v9, 1.0, v9
	v_pk_mul_f32 v[22:23], v[22:23], v[22:23]
	v_sub_f32_e32 v20, 1.0, v20
	v_sub_f32_e32 v21, 1.0, v21
	v_rcp_f32_e32 v8, v8
	v_rcp_f32_e32 v9, v9
	v_add_f32_e32 v10, 1.0, v10
	v_add_f32_e32 v11, 1.0, v11
	v_sqrt_f32_e32 v20, v20
	v_sub_f32_e32 v22, 1.0, v22
	v_sub_f32_e32 v23, 1.0, v23
	v_sqrt_f32_e32 v21, v21
	v_rcp_f32_e32 v10, v10
	v_rcp_f32_e32 v11, v11
	v_sqrt_f32_e32 v22, v22
	v_sqrt_f32_e32 v23, v23
	v_add_f32_e32 v4, 1.0, v4
	v_add_f32_e32 v5, 1.0, v5
	v_add_f32_e32 v6, 1.0, v6
	v_add_f32_e32 v7, 1.0, v7
	v_rcp_f32_e32 v4, v4
	v_rcp_f32_e32 v5, v5
	v_rcp_f32_e32 v6, v6
	v_rcp_f32_e32 v7, v7
	global_store_dwordx4 v[28:29], v[16:19], off offset:16
	v_pk_mul_f32 v[8:9], v[8:9], v[20:21]
	v_lshlrev_b32_e32 v24, 16, v69
	v_lshlrev_b32_e32 v18, 16, v68
	v_and_b32_e32 v19, 0xffff0000, v68
	v_lshlrev_b64 v[16:17], 13, v[198:199]
	v_and_b32_e32 v25, 0xffff0000, v69
	v_pk_mul_f32 v[10:11], v[10:11], v[22:23]
	v_pk_mul_f32 v[8:9], v[8:9], v[18:19]
	v_pk_mul_f32 v[10:11], v[10:11], v[24:25]
	v_cvt_pk_bf16_f32 v8, v12, v8
	v_cvt_pk_bf16_f32 v9, v13, v9
	v_lshl_add_u64 v[12:13], s[92:93], 0, v[16:17]
	v_pk_mul_f32 v[6:7], v[66:67], v[6:7]
	v_pk_mul_f32 v[4:5], v[64:65], v[4:5]
	v_cvt_pk_bf16_f32 v10, v14, v10
	v_cvt_pk_bf16_f32 v11, v15, v11
	v_lshl_add_u64 v[12:13], v[12:13], 0, v[196:197]
	v_pk_add_f32 v[2:3], v[2:3], v[74:75]
	v_pk_add_f32 v[0:1], v[0:1], v[72:73]
	v_pk_mul_f32 v[6:7], v[6:7], s[62:63] op_sel_hi:[1,0]
	v_pk_mul_f32 v[4:5], v[4:5], s[62:63] op_sel_hi:[1,0]
	global_store_dwordx4 v[12:13], v[8:11], off
	v_mul_f32_e32 v0, 0xbfb8aa3b, v0
	v_mul_f32_e32 v1, 0xbfb8aa3b, v1
	v_mul_f32_e32 v2, 0xbfb8aa3b, v2
	v_mul_f32_e32 v3, 0xbfb8aa3b, v3
	v_exp_f32_e32 v10, v4
	v_exp_f32_e32 v14, v6
	v_exp_f32_e32 v15, v7
	v_exp_f32_e32 v11, v5
	v_exp_f32_e32 v0, v0
	v_exp_f32_e32 v1, v1
	v_exp_f32_e32 v2, v2
	v_exp_f32_e32 v3, v3
	v_pk_mul_f32 v[14:15], v[14:15], v[14:15]
	v_pk_mul_f32 v[10:11], v[10:11], v[10:11]
	v_add_f32_e32 v0, 1.0, v0
	v_add_f32_e32 v1, 1.0, v1
	v_add_f32_e32 v2, 1.0, v2
	v_add_f32_e32 v3, 1.0, v3
	v_sub_f32_e32 v10, 1.0, v10
	v_sub_f32_e32 v11, 1.0, v11
	v_sub_f32_e32 v14, 1.0, v14
	v_sub_f32_e32 v15, 1.0, v15
	v_rcp_f32_e32 v0, v0
	v_rcp_f32_e32 v1, v1
	v_rcp_f32_e32 v2, v2
	v_rcp_f32_e32 v3, v3
	v_sqrt_f32_e32 v10, v10
	v_sqrt_f32_e32 v14, v14
	v_sqrt_f32_e32 v15, v15
	v_sqrt_f32_e32 v11, v11
	v_lshlrev_b32_e32 v8, 16, v70
	v_and_b32_e32 v9, 0xffff0000, v70
	v_lshlrev_b32_e32 v16, 16, v71
	v_and_b32_e32 v17, 0xffff0000, v71
	v_pk_mul_f32 v[2:3], v[2:3], v[14:15]
	v_pk_mul_f32 v[0:1], v[0:1], v[10:11]
	v_pk_mul_f32 v[2:3], v[2:3], v[16:17]
	v_pk_mul_f32 v[0:1], v[0:1], v[8:9]
	s_nop 0
	v_cvt_pk_bf16_f32 v0, v4, v0
	v_cvt_pk_bf16_f32 v1, v5, v1
	v_cvt_pk_bf16_f32 v2, v6, v2
	v_cvt_pk_bf16_f32 v3, v7, v3
	global_store_dwordx4 v[12:13], v[0:3], off offset:16
	s_mov_b64 s[4:5], vcc
	s_waitcnt vmcnt(0)
	s_barrier
; __device__ __forceinline__ float bf_lo(unsigned w) { return __uint_as_float(w << 16); }
; __device__ __forceinline__ float bf_hi(unsigned w) { return __uint_as_float(w & 0xffff0000u); }
; __global__ void __launch_bounds__(NTHR, 2) hybrid_block_fwd(Args a) {
;     ...
;         const int c2 = gtid & 1023, chunk = (gtid >> 10) & (NCH - 1), b = gtid >> 16;
;         const size_t r0 = (size_t)b * SEQ + (size_t)chunk * CH_L;
;         const u32x2* pab = (const u32x2*)((const unsigned*)AF + r0 * LW) + c2;
;         f32x2 P = (f32x2){1.f, 1.f}, H = (f32x2){0.f, 0.f};
; #pragma unroll 32
;         for (int i = 0; i < CH_L; ++i) { const u32x2 q = pab[(size_t)i * (LW / 2)];
;             const f32x2 av = (f32x2){__builtin_amdgcn_exp2f(bf_lo(q.x)), __builtin_amdgcn_exp2f(bf_lo(q.y))}, bv = (f32x2){bf_hi(q.x), bf_hi(q.y)}; P = P * av; H = av * H + bv; }
;         ((f32x2*)(AGGP + (size_t)(b * NCH + chunk) * LW))[c2] = P; ((f32x2*)(AGGH + (size_t)(b * NCH + chunk) * LW))[c2] = H;
	v_and_b32_e32 v1, 3, v212
	v_lshrrev_b32_e32 v2, 2, v212
	v_lshrrev_b32_e32 v4, 6, v2
	v_and_b32_e32 v2, 63, v2
	s_lshl_b32 s32, s74, 8
	s_lshl_b32 s45, s27, 7
	s_lshl_b32 s63, s74, 1
	v_lshl_add_u32 v3, v4, 7, s32
	v_lshl_add_u32 v3, v1, 5, v3
	v_lshlrev_b32_e32 v3, 13, v3
	v_lshl_add_u32 v8, v2, 1, s45
	v_lshl_add_u32 v3, v8, 2, v3
	v_add_u32_e32 v7, s63, v4
	v_lshl_add_u32 v7, v7, 11, v8
	v_lshlrev_b32_e32 v7, 2, v7
	v_add_u32_e32 v24, 0x100000, v7
	s_mov_b64 s[76:77], s[92:93]
	s_add_u32 s78, s94, 0x100000
	s_addc_u32 s79, s95, 0
	global_load_dwordx2 v[32:33], v3, s[76:77]
	s_add_u32 s76, s76, 0x2000
	s_addc_u32 s77, s77, 0
	global_load_dwordx2 v[34:35], v3, s[76:77]
	s_add_u32 s76, s76, 0x2000
	s_addc_u32 s77, s77, 0
	global_load_dwordx2 v[36:37], v3, s[76:77]
	s_add_u32 s76, s76, 0x2000
	s_addc_u32 s77, s77, 0
	global_load_dwordx2 v[38:39], v3, s[76:77]
	s_add_u32 s76, s76, 0x2000
	s_addc_u32 s77, s77, 0
	global_load_dwordx2 v[40:41], v3, s[76:77]
	s_add_u32 s76, s76, 0x2000
	s_addc_u32 s77, s77, 0
	global_load_dwordx2 v[42:43], v3, s[76:77]
	s_add_u32 s76, s76, 0x2000
	s_addc_u32 s77, s77, 0
	global_load_dwordx2 v[44:45], v3, s[76:77]
	s_add_u32 s76, s76, 0x2000
	s_addc_u32 s77, s77, 0
	global_load_dwordx2 v[46:47], v3, s[76:77]
	s_add_u32 s76, s76, 0x2000
	s_addc_u32 s77, s77, 0
	global_load_dwordx2 v[48:49], v3, s[76:77]
	s_add_u32 s76, s76, 0x2000
	s_addc_u32 s77, s77, 0
	global_load_dwordx2 v[50:51], v3, s[76:77]
	s_add_u32 s76, s76, 0x2000
	s_addc_u32 s77, s77, 0
	global_load_dwordx2 v[52:53], v3, s[76:77]
	s_add_u32 s76, s76, 0x2000
	s_addc_u32 s77, s77, 0
	global_load_dwordx2 v[54:55], v3, s[76:77]
	s_add_u32 s76, s76, 0x2000
	s_addc_u32 s77, s77, 0
	global_load_dwordx2 v[56:57], v3, s[76:77]
	s_add_u32 s76, s76, 0x2000
	s_addc_u32 s77, s77, 0
	global_load_dwordx2 v[58:59], v3, s[76:77]
	s_add_u32 s76, s76, 0x2000
	s_addc_u32 s77, s77, 0
	global_load_dwordx2 v[60:61], v3, s[76:77]
	s_add_u32 s76, s76, 0x2000
	s_addc_u32 s77, s77, 0
	global_load_dwordx2 v[62:63], v3, s[76:77]
	s_add_u32 s76, s76, 0x2000
	s_addc_u32 s77, s77, 0
	global_load_dwordx2 v[64:65], v3, s[76:77]
	s_add_u32 s76, s76, 0x2000
	s_addc_u32 s77, s77, 0
	global_load_dwordx2 v[66:67], v3, s[76:77]
	s_add_u32 s76, s76, 0x2000
	s_addc_u32 s77, s77, 0
	global_load_dwordx2 v[68:69], v3, s[76:77]
	s_add_u32 s76, s76, 0x2000
	s_addc_u32 s77, s77, 0
	global_load_dwordx2 v[70:71], v3, s[76:77]
	s_add_u32 s76, s76, 0x2000
	s_addc_u32 s77, s77, 0
	global_load_dwordx2 v[72:73], v3, s[76:77]
	s_add_u32 s76, s76, 0x2000
	s_addc_u32 s77, s77, 0
	global_load_dwordx2 v[74:75], v3, s[76:77]
	s_add_u32 s76, s76, 0x2000
	s_addc_u32 s77, s77, 0
	global_load_dwordx2 v[76:77], v3, s[76:77]
	s_add_u32 s76, s76, 0x2000
	s_addc_u32 s77, s77, 0
	global_load_dwordx2 v[78:79], v3, s[76:77]
	s_add_u32 s76, s76, 0x2000
	s_addc_u32 s77, s77, 0
	global_load_dwordx2 v[80:81], v3, s[76:77]
	s_add_u32 s76, s76, 0x2000
	s_addc_u32 s77, s77, 0
	global_load_dwordx2 v[82:83], v3, s[76:77]
	s_add_u32 s76, s76, 0x2000
	s_addc_u32 s77, s77, 0
	global_load_dwordx2 v[84:85], v3, s[76:77]
	s_add_u32 s76, s76, 0x2000
	s_addc_u32 s77, s77, 0
	global_load_dwordx2 v[86:87], v3, s[76:77]
	s_add_u32 s76, s76, 0x2000
	s_addc_u32 s77, s77, 0
	global_load_dwordx2 v[88:89], v3, s[76:77]
	s_add_u32 s76, s76, 0x2000
	s_addc_u32 s77, s77, 0
	global_load_dwordx2 v[90:91], v3, s[76:77]
	s_add_u32 s76, s76, 0x2000
	s_addc_u32 s77, s77, 0
	global_load_dwordx2 v[92:93], v3, s[76:77]
	s_add_u32 s76, s76, 0x2000
	s_addc_u32 s77, s77, 0
	global_load_dwordx2 v[94:95], v3, s[76:77]
	v_mov_b32_e32 v28, 1.0
	v_mov_b32_e32 v29, 1.0
	v_mov_b32_e32 v30, 0
	v_mov_b32_e32 v31, 0
	s_waitcnt vmcnt(28)
	v_lshlrev_b32_e32 v100, 16, v32
	v_lshlrev_b32_e32 v101, 16, v33
	v_lshlrev_b32_e32 v104, 16, v34
	v_lshlrev_b32_e32 v105, 16, v35
	v_lshlrev_b32_e32 v108, 16, v36
	v_lshlrev_b32_e32 v109, 16, v37
	v_lshlrev_b32_e32 v112, 16, v38
	v_lshlrev_b32_e32 v113, 16, v39
	v_and_b32_e32 v102, 0xffff0000, v32
	v_and_b32_e32 v103, 0xffff0000, v33
	v_and_b32_e32 v106, 0xffff0000, v34
	v_and_b32_e32 v107, 0xffff0000, v35
	v_and_b32_e32 v110, 0xffff0000, v36
	v_and_b32_e32 v111, 0xffff0000, v37
	v_and_b32_e32 v114, 0xffff0000, v38
	v_and_b32_e32 v115, 0xffff0000, v39
	v_exp_f32_e32 v100, v100
	v_exp_f32_e32 v101, v101
	v_exp_f32_e32 v104, v104
	v_exp_f32_e32 v105, v105
	v_exp_f32_e32 v108, v108
	v_exp_f32_e32 v109, v109
	v_exp_f32_e32 v112, v112
	v_exp_f32_e32 v113, v113
	v_mul_f32_e32 v28, v28, v100
	v_fma_f32 v30, v30, v100, v102
	v_mul_f32_e32 v29, v29, v101
	v_fma_f32 v31, v31, v101, v103
	v_mul_f32_e32 v28, v28, v104
	v_fma_f32 v30, v30, v104, v106
	v_mul_f32_e32 v29, v29, v105
	v_fma_f32 v31, v31, v105, v107
	v_mul_f32_e32 v28, v28, v108
	v_fma_f32 v30, v30, v108, v110
	v_mul_f32_e32 v29, v29, v109
	v_fma_f32 v31, v31, v109, v111
	v_mul_f32_e32 v28, v28, v112
	v_fma_f32 v30, v30, v112, v114
	v_mul_f32_e32 v29, v29, v113
	v_fma_f32 v31, v31, v113, v115
	s_waitcnt vmcnt(24)
	v_lshlrev_b32_e32 v120, 16, v40
	v_lshlrev_b32_e32 v121, 16, v41
	v_lshlrev_b32_e32 v124, 16, v42
	v_lshlrev_b32_e32 v125, 16, v43
	v_lshlrev_b32_e32 v128, 16, v44
	v_lshlrev_b32_e32 v129, 16, v45
	v_lshlrev_b32_e32 v132, 16, v46
	v_lshlrev_b32_e32 v133, 16, v47
	v_and_b32_e32 v122, 0xffff0000, v40
	v_and_b32_e32 v123, 0xffff0000, v41
	v_and_b32_e32 v126, 0xffff0000, v42
	v_and_b32_e32 v127, 0xffff0000, v43
	v_and_b32_e32 v130, 0xffff0000, v44
	v_and_b32_e32 v131, 0xffff0000, v45
	v_and_b32_e32 v134, 0xffff0000, v46
	v_and_b32_e32 v135, 0xffff0000, v47
	v_exp_f32_e32 v120, v120
	v_exp_f32_e32 v121, v121
	v_exp_f32_e32 v124, v124
	v_exp_f32_e32 v125, v125
	v_exp_f32_e32 v128, v128
	v_exp_f32_e32 v129, v129
	v_exp_f32_e32 v132, v132
	v_exp_f32_e32 v133, v133
	v_mul_f32_e32 v28, v28, v120
	v_fma_f32 v30, v30, v120, v122
	v_mul_f32_e32 v29, v29, v121
	v_fma_f32 v31, v31, v121, v123
	v_mul_f32_e32 v28, v28, v124
	v_fma_f32 v30, v30, v124, v126
	v_mul_f32_e32 v29, v29, v125
	v_fma_f32 v31, v31, v125, v127
	v_mul_f32_e32 v28, v28, v128
	v_fma_f32 v30, v30, v128, v130
	v_mul_f32_e32 v29, v29, v129
	v_fma_f32 v31, v31, v129, v131
	v_mul_f32_e32 v28, v28, v132
	v_fma_f32 v30, v30, v132, v134
	v_mul_f32_e32 v29, v29, v133
	v_fma_f32 v31, v31, v133, v135
	s_waitcnt vmcnt(20)
; __device__ __forceinline__ float bf_lo(unsigned w) { return __uint_as_float(w << 16); }
; __device__ __forceinline__ float bf_hi(unsigned w) { return __uint_as_float(w & 0xffff0000u); }
; __global__ void __launch_bounds__(NTHR, 2) hybrid_block_fwd(Args a) {
;     ...
;         for (int i = 0; i < CH_L; ++i) { const u32x2 q = pab[(size_t)i * (LW / 2)];
;             const f32x2 av = (f32x2){__builtin_amdgcn_exp2f(bf_lo(q.x)), __builtin_amdgcn_exp2f(bf_lo(q.y))}, bv = (f32x2){bf_hi(q.x), bf_hi(q.y)}; P = P * av; H = av * H + bv; }
	v_lshlrev_b32_e32 v100, 16, v48
	v_lshlrev_b32_e32 v101, 16, v49
	v_lshlrev_b32_e32 v104, 16, v50
	v_lshlrev_b32_e32 v105, 16, v51
	v_lshlrev_b32_e32 v108, 16, v52
	v_lshlrev_b32_e32 v109, 16, v53
	v_lshlrev_b32_e32 v112, 16, v54
	v_lshlrev_b32_e32 v113, 16, v55
	v_and_b32_e32 v102, 0xffff0000, v48
	v_and_b32_e32 v103, 0xffff0000, v49
	v_and_b32_e32 v106, 0xffff0000, v50
	v_and_b32_e32 v107, 0xffff0000, v51
	v_and_b32_e32 v110, 0xffff0000, v52
	v_and_b32_e32 v111, 0xffff0000, v53
	v_and_b32_e32 v114, 0xffff0000, v54
	v_and_b32_e32 v115, 0xffff0000, v55
	v_exp_f32_e32 v100, v100
	v_exp_f32_e32 v101, v101
	v_exp_f32_e32 v104, v104
	v_exp_f32_e32 v105, v105
	v_exp_f32_e32 v108, v108
	v_exp_f32_e32 v109, v109
	v_exp_f32_e32 v112, v112
	v_exp_f32_e32 v113, v113
	v_mul_f32_e32 v28, v28, v100
	v_fma_f32 v30, v30, v100, v102
	v_mul_f32_e32 v29, v29, v101
	v_fma_f32 v31, v31, v101, v103
	v_mul_f32_e32 v28, v28, v104
	v_fma_f32 v30, v30, v104, v106
	v_mul_f32_e32 v29, v29, v105
	v_fma_f32 v31, v31, v105, v107
	v_mul_f32_e32 v28, v28, v108
	v_fma_f32 v30, v30, v108, v110
	v_mul_f32_e32 v29, v29, v109
	v_fma_f32 v31, v31, v109, v111
	v_mul_f32_e32 v28, v28, v112
	v_fma_f32 v30, v30, v112, v114
	v_mul_f32_e32 v29, v29, v113
	v_fma_f32 v31, v31, v113, v115
	s_waitcnt vmcnt(16)
	v_lshlrev_b32_e32 v120, 16, v56
	v_lshlrev_b32_e32 v121, 16, v57
	v_lshlrev_b32_e32 v124, 16, v58
	v_lshlrev_b32_e32 v125, 16, v59
	v_lshlrev_b32_e32 v128, 16, v60
	v_lshlrev_b32_e32 v129, 16, v61
	v_lshlrev_b32_e32 v132, 16, v62
	v_lshlrev_b32_e32 v133, 16, v63
	v_and_b32_e32 v122, 0xffff0000, v56
	v_and_b32_e32 v123, 0xffff0000, v57
	v_and_b32_e32 v126, 0xffff0000, v58
	v_and_b32_e32 v127, 0xffff0000, v59
	v_and_b32_e32 v130, 0xffff0000, v60
	v_and_b32_e32 v131, 0xffff0000, v61
	v_and_b32_e32 v134, 0xffff0000, v62
	v_and_b32_e32 v135, 0xffff0000, v63
	v_exp_f32_e32 v120, v120
	v_exp_f32_e32 v121, v121
	v_exp_f32_e32 v124, v124
	v_exp_f32_e32 v125, v125
	v_exp_f32_e32 v128, v128
	v_exp_f32_e32 v129, v129
	v_exp_f32_e32 v132, v132
	v_exp_f32_e32 v133, v133
	v_mul_f32_e32 v28, v28, v120
	v_fma_f32 v30, v30, v120, v122
	v_mul_f32_e32 v29, v29, v121
	v_fma_f32 v31, v31, v121, v123
	v_mul_f32_e32 v28, v28, v124
	v_fma_f32 v30, v30, v124, v126
	v_mul_f32_e32 v29, v29, v125
	v_fma_f32 v31, v31, v125, v127
	v_mul_f32_e32 v28, v28, v128
	v_fma_f32 v30, v30, v128, v130
	v_mul_f32_e32 v29, v29, v129
	v_fma_f32 v31, v31, v129, v131
	v_mul_f32_e32 v28, v28, v132
	v_fma_f32 v30, v30, v132, v134
	v_mul_f32_e32 v29, v29, v133
	v_fma_f32 v31, v31, v133, v135
	s_waitcnt vmcnt(12)
	v_lshlrev_b32_e32 v100, 16, v64
	v_lshlrev_b32_e32 v101, 16, v65
	v_lshlrev_b32_e32 v104, 16, v66
	v_lshlrev_b32_e32 v105, 16, v67
	v_lshlrev_b32_e32 v108, 16, v68
	v_lshlrev_b32_e32 v109, 16, v69
	v_lshlrev_b32_e32 v112, 16, v70
	v_lshlrev_b32_e32 v113, 16, v71
	v_and_b32_e32 v102, 0xffff0000, v64
	v_and_b32_e32 v103, 0xffff0000, v65
	v_and_b32_e32 v106, 0xffff0000, v66
	v_and_b32_e32 v107, 0xffff0000, v67
	v_and_b32_e32 v110, 0xffff0000, v68
	v_and_b32_e32 v111, 0xffff0000, v69
	v_and_b32_e32 v114, 0xffff0000, v70
	v_and_b32_e32 v115, 0xffff0000, v71
	v_exp_f32_e32 v100, v100
	v_exp_f32_e32 v101, v101
	v_exp_f32_e32 v104, v104
	v_exp_f32_e32 v105, v105
	v_exp_f32_e32 v108, v108
	v_exp_f32_e32 v109, v109
	v_exp_f32_e32 v112, v112
	v_exp_f32_e32 v113, v113
	v_mul_f32_e32 v28, v28, v100
	v_fma_f32 v30, v30, v100, v102
	v_mul_f32_e32 v29, v29, v101
	v_fma_f32 v31, v31, v101, v103
	v_mul_f32_e32 v28, v28, v104
	v_fma_f32 v30, v30, v104, v106
	v_mul_f32_e32 v29, v29, v105
	v_fma_f32 v31, v31, v105, v107
	v_mul_f32_e32 v28, v28, v108
	v_fma_f32 v30, v30, v108, v110
	v_mul_f32_e32 v29, v29, v109
	v_fma_f32 v31, v31, v109, v111
	v_mul_f32_e32 v28, v28, v112
	v_fma_f32 v30, v30, v112, v114
	v_mul_f32_e32 v29, v29, v113
	v_fma_f32 v31, v31, v113, v115
	s_waitcnt vmcnt(8)
; __device__ __forceinline__ float bf_lo(unsigned w) { return __uint_as_float(w << 16); }
; __device__ __forceinline__ float bf_hi(unsigned w) { return __uint_as_float(w & 0xffff0000u); }
; #define PG8_BAR __builtin_amdgcn_s_barrier()
; template <class Epi, class Sched>
; __device__ __forceinline__ void gemm_phase(LAS unsigned char* lds, const Gemm g, const Sched& S, const Epi& E) {
;     ...
;         if (!has_next) break;
; #pragma unroll
;         for (int a = 0; a < 2; ++a)
; #pragma unroll
;             for (int b = 0; b < 2; ++b)
; #pragma unroll
;                 for (int m = 0; m < 4; ++m)
; #pragma unroll
;                     for (int n = 0; n < 2; ++n) acc[a][b][m][n] = (f32x4){0.f, 0.f, 0.f, 0.f};
;         cur = nxt; cA = nA; cB = nB; ++ui;
;         if (wr == 1) PG8_BAR;
; __global__ void __launch_bounds__(NTHR, 2) hybrid_block_fwd(Args a) {
;     ...
;         for (int i = 0; i < CH_L; ++i) { const u32x2 q = pab[(size_t)i * (LW / 2)];
;             const f32x2 av = (f32x2){__builtin_amdgcn_exp2f(bf_lo(q.x)), __builtin_amdgcn_exp2f(bf_lo(q.y))}, bv = (f32x2){bf_hi(q.x), bf_hi(q.y)}; P = P * av; H = av * H + bv; }
;         ((f32x2*)(AGGP + (size_t)(b * NCH + chunk) * LW))[c2] = P; ((f32x2*)(AGGH + (size_t)(b * NCH + chunk) * LW))[c2] = H;
	v_lshlrev_b32_e32 v120, 16, v72
	v_lshlrev_b32_e32 v121, 16, v73
	v_lshlrev_b32_e32 v124, 16, v74
	v_lshlrev_b32_e32 v125, 16, v75
	v_lshlrev_b32_e32 v128, 16, v76
	v_lshlrev_b32_e32 v129, 16, v77
	v_lshlrev_b32_e32 v132, 16, v78
	v_lshlrev_b32_e32 v133, 16, v79
	v_and_b32_e32 v122, 0xffff0000, v72
	v_and_b32_e32 v123, 0xffff0000, v73
	v_and_b32_e32 v126, 0xffff0000, v74
	v_and_b32_e32 v127, 0xffff0000, v75
	v_and_b32_e32 v130, 0xffff0000, v76
	v_and_b32_e32 v131, 0xffff0000, v77
	v_and_b32_e32 v134, 0xffff0000, v78
	v_and_b32_e32 v135, 0xffff0000, v79
	v_exp_f32_e32 v120, v120
	v_exp_f32_e32 v121, v121
	v_exp_f32_e32 v124, v124
	v_exp_f32_e32 v125, v125
	v_exp_f32_e32 v128, v128
	v_exp_f32_e32 v129, v129
	v_exp_f32_e32 v132, v132
	v_exp_f32_e32 v133, v133
	v_mul_f32_e32 v28, v28, v120
	v_fma_f32 v30, v30, v120, v122
	v_mul_f32_e32 v29, v29, v121
	v_fma_f32 v31, v31, v121, v123
	v_mul_f32_e32 v28, v28, v124
	v_fma_f32 v30, v30, v124, v126
	v_mul_f32_e32 v29, v29, v125
	v_fma_f32 v31, v31, v125, v127
	v_mul_f32_e32 v28, v28, v128
	v_fma_f32 v30, v30, v128, v130
	v_mul_f32_e32 v29, v29, v129
	v_fma_f32 v31, v31, v129, v131
	v_mul_f32_e32 v28, v28, v132
	v_fma_f32 v30, v30, v132, v134
	v_mul_f32_e32 v29, v29, v133
	v_fma_f32 v31, v31, v133, v135
	s_waitcnt vmcnt(4)
	v_lshlrev_b32_e32 v100, 16, v80
	v_lshlrev_b32_e32 v101, 16, v81
	v_lshlrev_b32_e32 v104, 16, v82
	v_lshlrev_b32_e32 v105, 16, v83
	v_lshlrev_b32_e32 v108, 16, v84
	v_lshlrev_b32_e32 v109, 16, v85
	v_lshlrev_b32_e32 v112, 16, v86
	v_lshlrev_b32_e32 v113, 16, v87
	v_and_b32_e32 v102, 0xffff0000, v80
	v_and_b32_e32 v103, 0xffff0000, v81
	v_and_b32_e32 v106, 0xffff0000, v82
	v_and_b32_e32 v107, 0xffff0000, v83
	v_and_b32_e32 v110, 0xffff0000, v84
	v_and_b32_e32 v111, 0xffff0000, v85
	v_and_b32_e32 v114, 0xffff0000, v86
	v_and_b32_e32 v115, 0xffff0000, v87
	v_exp_f32_e32 v100, v100
	v_exp_f32_e32 v101, v101
	v_exp_f32_e32 v104, v104
	v_exp_f32_e32 v105, v105
	v_exp_f32_e32 v108, v108
	v_exp_f32_e32 v109, v109
	v_exp_f32_e32 v112, v112
	v_exp_f32_e32 v113, v113
	v_mul_f32_e32 v28, v28, v100
	v_fma_f32 v30, v30, v100, v102
	v_mul_f32_e32 v29, v29, v101
	v_fma_f32 v31, v31, v101, v103
	v_mul_f32_e32 v28, v28, v104
	v_fma_f32 v30, v30, v104, v106
	v_mul_f32_e32 v29, v29, v105
	v_fma_f32 v31, v31, v105, v107
	v_mul_f32_e32 v28, v28, v108
	v_fma_f32 v30, v30, v108, v110
	v_mul_f32_e32 v29, v29, v109
	v_fma_f32 v31, v31, v109, v111
	v_mul_f32_e32 v28, v28, v112
	v_fma_f32 v30, v30, v112, v114
	v_mul_f32_e32 v29, v29, v113
	v_fma_f32 v31, v31, v113, v115
	s_waitcnt vmcnt(0)
	v_lshlrev_b32_e32 v120, 16, v88
	v_lshlrev_b32_e32 v121, 16, v89
	v_lshlrev_b32_e32 v124, 16, v90
	v_lshlrev_b32_e32 v125, 16, v91
	v_lshlrev_b32_e32 v128, 16, v92
	v_lshlrev_b32_e32 v129, 16, v93
	v_lshlrev_b32_e32 v132, 16, v94
	v_lshlrev_b32_e32 v133, 16, v95
	v_and_b32_e32 v122, 0xffff0000, v88
	v_and_b32_e32 v123, 0xffff0000, v89
	v_and_b32_e32 v126, 0xffff0000, v90
	v_and_b32_e32 v127, 0xffff0000, v91
	v_and_b32_e32 v130, 0xffff0000, v92
	v_and_b32_e32 v131, 0xffff0000, v93
	v_and_b32_e32 v134, 0xffff0000, v94
	v_and_b32_e32 v135, 0xffff0000, v95
	v_exp_f32_e32 v120, v120
	v_exp_f32_e32 v121, v121
	v_exp_f32_e32 v124, v124
	v_exp_f32_e32 v125, v125
	v_exp_f32_e32 v128, v128
	v_exp_f32_e32 v129, v129
	v_exp_f32_e32 v132, v132
	v_exp_f32_e32 v133, v133
	v_mul_f32_e32 v28, v28, v120
	v_fma_f32 v30, v30, v120, v122
	v_mul_f32_e32 v29, v29, v121
	v_fma_f32 v31, v31, v121, v123
	v_mul_f32_e32 v28, v28, v124
	v_fma_f32 v30, v30, v124, v126
	v_mul_f32_e32 v29, v29, v125
	v_fma_f32 v31, v31, v125, v127
	v_mul_f32_e32 v28, v28, v128
	v_fma_f32 v30, v30, v128, v130
	v_mul_f32_e32 v29, v29, v129
	v_fma_f32 v31, v31, v129, v131
	v_mul_f32_e32 v28, v28, v132
	v_fma_f32 v30, v30, v132, v134
	v_mul_f32_e32 v29, v29, v133
	v_fma_f32 v31, v31, v133, v135
	s_nop 1
	v_fmac_f32_dpp v30, v30, v28 row_shr:1 row_mask:0xf bank_mask:0xf
	v_fmac_f32_dpp v31, v31, v29 row_shr:1 row_mask:0xf bank_mask:0xf
	v_mul_f32_dpp v28, v28, v28 row_shr:1 row_mask:0xf bank_mask:0xf
	v_mul_f32_dpp v29, v29, v29 row_shr:1 row_mask:0xf bank_mask:0xf
	s_nop 1
	v_fmac_f32_dpp v30, v30, v28 row_shr:2 row_mask:0xf bank_mask:0xf
	v_fmac_f32_dpp v31, v31, v29 row_shr:2 row_mask:0xf bank_mask:0xf
	v_mul_f32_dpp v28, v28, v28 row_shr:2 row_mask:0xf bank_mask:0xf
	v_mul_f32_dpp v29, v29, v29 row_shr:2 row_mask:0xf bank_mask:0xf
	v_cmp_eq_u32_e32 vcc, 3, v1
	s_and_saveexec_b64 s[22:23], vcc
	global_store_dwordx2 v7, v[28:29], s[78:79]
	global_store_dwordx2 v24, v[30:31], s[78:79]
	s_or_b64 exec, exec, s[22:23]
	s_mov_b64 vcc, s[4:5]
	s_cbranch_vccnz .LBB0_543
	s_andn2_b64 vcc, exec, s[10:11]
	s_cbranch_vccnz .LBB0_542
	s_barrier
	s_branch .LBB0_542
